# EpiConv (w_up epilogue): merge 4 scattered dword stores per row group into one dwordx4 store
# speedup vs baseline: 1.0169x; 1.0099x over previous
.LBB0_715:
	s_or_b64 exec, exec, s[56:57]
	v_mov_b32_e32 v242, 0
	v_mov_b32_e32 v193, 0
	v_mov_b32_e32 v243, 0
	s_waitcnt lgkmcnt(0)
	v_mov_b32_dpp v242, v198 row_ror:2 row_mask:0xf bank_mask:0xf
	v_mov_b32_dpp v193, v198 row_ror:1 row_mask:0xf bank_mask:0xf
	v_mov_b32_e32 v198, 0
	v_mov_b32_dpp v242, v188 row_shr:2 row_mask:0xf bank_mask:0xf
	v_mov_b32_dpp v193, v188 row_shr:1 row_mask:0xf bank_mask:0xf
	s_waitcnt vmcnt(0)
	v_fma_f32 v242, v164, v242, v156
	v_fmac_f32_e32 v242, v168, v193
	v_fmac_f32_e32 v242, v188, v172
	v_mul_f32_e32 v193, 0xbfb8aa3b, v242
	v_exp_f32_e32 v193, v193
	v_mov_b32_dpp v243, v194 row_ror:2 row_mask:0xf bank_mask:0xf
	v_mov_b32_dpp v198, v194 row_ror:1 row_mask:0xf bank_mask:0xf
	v_lshl_add_u32 v210, s54, 8, v213
	v_add_f32_e32 v193, 1.0, v193
	v_rcp_f32_e32 v193, v193
	v_mov_b32_dpp v243, v184 row_shr:2 row_mask:0xf bank_mask:0xf
	v_mov_b32_dpp v198, v184 row_shr:1 row_mask:0xf bank_mask:0xf
	v_fma_f32 v194, v144, v243, v160
	v_fmac_f32_e32 v194, v148, v198
	v_fmac_f32_e32 v194, v184, v152
	v_mul_f32_e32 v193, v242, v193
	v_mov_b32_e32 v198, 0
	v_mul_f32_e32 v193, v194, v193
	v_mov_b32_e32 v194, 0
	v_mov_b32_dpp v198, v199 row_ror:2 row_mask:0xf bank_mask:0xf
	v_mov_b32_e32 v242, 0
	v_mov_b32_dpp v194, v199 row_ror:1 row_mask:0xf bank_mask:0xf
	v_mov_b32_dpp v198, v189 row_shr:2 row_mask:0xf bank_mask:0xf
	v_fma_f32 v198, v165, v198, v157
	v_mov_b32_dpp v194, v189 row_shr:1 row_mask:0xf bank_mask:0xf
	v_fmac_f32_e32 v198, v169, v194
	v_fmac_f32_e32 v198, v189, v173
	v_mul_f32_e32 v194, 0xbfb8aa3b, v198
	v_exp_f32_e32 v194, v194
	v_mov_b32_e32 v199, 0
	v_mov_b32_dpp v242, v195 row_ror:2 row_mask:0xf bank_mask:0xf
	v_add_f32_e32 v194, 1.0, v194
	v_rcp_f32_e32 v194, v194
	v_mov_b32_dpp v199, v195 row_ror:1 row_mask:0xf bank_mask:0xf
	v_mov_b32_dpp v242, v185 row_shr:2 row_mask:0xf bank_mask:0xf
	v_fma_f32 v195, v145, v242, v161
	v_mov_b32_dpp v199, v185 row_shr:1 row_mask:0xf bank_mask:0xf
	v_fmac_f32_e32 v195, v149, v199
	v_fmac_f32_e32 v195, v185, v153
	v_mul_f32_e32 v194, v198, v194
	v_mul_f32_e32 v242, v195, v194
	v_mov_b32_e32 v195, 0
	v_mov_b32_e32 v194, 0
	v_mov_b32_e32 v199, 0
	v_mov_b32_dpp v195, v200 row_ror:2 row_mask:0xf bank_mask:0xf
	v_mov_b32_dpp v194, v200 row_ror:1 row_mask:0xf bank_mask:0xf
	v_mov_b32_e32 v198, 0
	v_mov_b32_dpp v195, v190 row_shr:2 row_mask:0xf bank_mask:0xf
	v_mov_b32_dpp v194, v190 row_shr:1 row_mask:0xf bank_mask:0xf
	v_fma_f32 v195, v166, v195, v158
	v_fmac_f32_e32 v195, v170, v194
	v_fmac_f32_e32 v195, v190, v174
	v_mul_f32_e32 v194, 0xbfb8aa3b, v195
	v_exp_f32_e32 v194, v194
	v_mov_b32_dpp v199, v196 row_ror:2 row_mask:0xf bank_mask:0xf
	v_mov_b32_dpp v198, v196 row_ror:1 row_mask:0xf bank_mask:0xf
	v_cvt_pk_bf16_f32 v244, v193, v242
	v_add_f32_e32 v194, 1.0, v194
	v_rcp_f32_e32 v194, v194
	v_mov_b32_dpp v199, v186 row_shr:2 row_mask:0xf bank_mask:0xf
	v_mov_b32_dpp v198, v186 row_shr:1 row_mask:0xf bank_mask:0xf
	v_fma_f32 v196, v146, v199, v162
	v_fmac_f32_e32 v196, v150, v198
	v_fmac_f32_e32 v196, v186, v154
	v_mul_f32_e32 v194, v195, v194
	v_mov_b32_e32 v195, 0
	v_mul_f32_e32 v200, v196, v194
	v_mov_b32_e32 v194, 0
	v_mov_b32_dpp v195, v201 row_ror:2 row_mask:0xf bank_mask:0xf
	v_mov_b32_e32 v198, 0
	v_mov_b32_dpp v194, v201 row_ror:1 row_mask:0xf bank_mask:0xf
	v_mov_b32_dpp v195, v191 row_shr:2 row_mask:0xf bank_mask:0xf
	v_fma_f32 v195, v167, v195, v159
	v_mov_b32_dpp v194, v191 row_shr:1 row_mask:0xf bank_mask:0xf
	v_fmac_f32_e32 v195, v171, v194
	v_fmac_f32_e32 v195, v191, v175
	v_mul_f32_e32 v194, 0xbfb8aa3b, v195
	v_exp_f32_e32 v194, v194
	v_mov_b32_e32 v196, 0
	v_mov_b32_dpp v198, v197 row_ror:2 row_mask:0xf bank_mask:0xf
	v_add_f32_e32 v194, 1.0, v194
	v_rcp_f32_e32 v194, v194
	v_mov_b32_dpp v196, v197 row_ror:1 row_mask:0xf bank_mask:0xf
	v_mov_b32_dpp v198, v187 row_shr:2 row_mask:0xf bank_mask:0xf
	v_fma_f32 v197, v147, v198, v163
	v_mov_b32_dpp v196, v187 row_shr:1 row_mask:0xf bank_mask:0xf
	v_fmac_f32_e32 v197, v151, v196
	v_fmac_f32_e32 v197, v187, v155
	v_mul_f32_e32 v194, v195, v194
	v_mul_f32_e32 v201, v197, v194
	v_mov_b64_e32 v[194:195], s[12:13]
	v_mad_i64_i32 v[196:197], s[54:55], v210, s77, v[194:195]
	v_lshlrev_b64 v[198:199], 1, v[226:227]
	v_lshl_add_u64 v[196:197], v[196:197], 0, v[198:199]
	v_cvt_pk_bf16_f32 v245, v200, v201
	v_mov_b32_e32 v200, 0
	v_mov_b32_e32 v193, 0
	v_mov_b32_dpp v200, v188 row_ror:2 row_mask:0xf bank_mask:0xf
	v_mov_b32_e32 v201, 0
	v_mov_b32_dpp v193, v188 row_ror:1 row_mask:0xf bank_mask:0xf
	v_mov_b32_dpp v200, v180 row_shr:2 row_mask:0xf bank_mask:0xf
	v_fma_f32 v200, v164, v200, v156
	v_mov_b32_dpp v193, v180 row_shr:1 row_mask:0xf bank_mask:0xf
	v_fmac_f32_e32 v200, v168, v193
	v_fmac_f32_e32 v200, v180, v172
	v_mul_f32_e32 v193, 0xbfb8aa3b, v200
	v_exp_f32_e32 v193, v193
	v_mov_b32_e32 v188, 0
	v_mov_b32_dpp v201, v184 row_ror:2 row_mask:0xf bank_mask:0xf
	s_nop 0
	v_mov_b32_dpp v188, v184 row_ror:1 row_mask:0xf bank_mask:0xf
	v_add_f32_e32 v184, 1.0, v193
	v_rcp_f32_e32 v184, v184
	v_mov_b32_dpp v201, v176 row_shr:2 row_mask:0xf bank_mask:0xf
	v_mov_b32_dpp v188, v176 row_shr:1 row_mask:0xf bank_mask:0xf
	v_fma_f32 v193, v144, v201, v160
	v_fmac_f32_e32 v193, v148, v188
	v_fmac_f32_e32 v193, v176, v152
	v_mul_f32_e32 v184, v200, v184
	v_mul_f32_e32 v188, v193, v184
	v_mov_b32_e32 v193, 0
	v_mov_b32_e32 v184, 0
	v_mov_b32_e32 v200, 0
	v_mov_b32_dpp v193, v189 row_ror:2 row_mask:0xf bank_mask:0xf
	v_mov_b32_dpp v184, v189 row_ror:1 row_mask:0xf bank_mask:0xf
	v_mov_b32_e32 v189, 0
	v_mov_b32_dpp v193, v181 row_shr:2 row_mask:0xf bank_mask:0xf
	v_mov_b32_dpp v184, v181 row_shr:1 row_mask:0xf bank_mask:0xf
	v_fma_f32 v193, v165, v193, v157
	v_fmac_f32_e32 v193, v169, v184
	v_fmac_f32_e32 v193, v181, v173
	v_mul_f32_e32 v184, 0xbfb8aa3b, v193
	v_exp_f32_e32 v184, v184
	v_mov_b32_dpp v200, v185 row_ror:2 row_mask:0xf bank_mask:0xf
	v_mov_b32_dpp v189, v185 row_ror:1 row_mask:0xf bank_mask:0xf
	v_add_f32_e32 v184, 1.0, v184
	v_rcp_f32_e32 v184, v184
	v_mov_b32_dpp v200, v177 row_shr:2 row_mask:0xf bank_mask:0xf
	v_mov_b32_dpp v189, v177 row_shr:1 row_mask:0xf bank_mask:0xf
	v_fma_f32 v185, v145, v200, v161
	v_fmac_f32_e32 v185, v149, v189
	v_fmac_f32_e32 v185, v177, v153
	v_mul_f32_e32 v184, v193, v184
	v_mul_f32_e32 v189, v185, v184
	v_mov_b32_e32 v185, 0
	v_mov_b32_e32 v184, 0
	v_mov_b32_e32 v193, 0
	v_mov_b32_dpp v185, v190 row_ror:2 row_mask:0xf bank_mask:0xf
	v_mov_b32_dpp v184, v190 row_ror:1 row_mask:0xf bank_mask:0xf
	v_mov_b32_e32 v190, 0
	v_mov_b32_dpp v185, v182 row_shr:2 row_mask:0xf bank_mask:0xf
	v_mov_b32_dpp v184, v182 row_shr:1 row_mask:0xf bank_mask:0xf
	v_fma_f32 v185, v166, v185, v158
	v_fmac_f32_e32 v185, v170, v184
	v_fmac_f32_e32 v185, v182, v174
	v_mul_f32_e32 v184, 0xbfb8aa3b, v185
	v_exp_f32_e32 v184, v184
	v_mov_b32_dpp v193, v186 row_ror:2 row_mask:0xf bank_mask:0xf
	v_mov_b32_dpp v190, v186 row_ror:1 row_mask:0xf bank_mask:0xf
	v_cvt_pk_bf16_f32 v242, v188, v189
	v_add_f32_e32 v184, 1.0, v184
	v_rcp_f32_e32 v184, v184
	v_mov_b32_dpp v193, v178 row_shr:2 row_mask:0xf bank_mask:0xf
	v_mov_b32_dpp v190, v178 row_shr:1 row_mask:0xf bank_mask:0xf
	v_fma_f32 v186, v146, v193, v162
	v_fmac_f32_e32 v186, v150, v190
	v_fmac_f32_e32 v186, v178, v154
	v_mul_f32_e32 v184, v185, v184
	v_mov_b32_e32 v185, 0
	v_mul_f32_e32 v186, v186, v184
	v_mov_b32_e32 v184, 0
	v_mov_b32_dpp v185, v191 row_ror:2 row_mask:0xf bank_mask:0xf
	v_mov_b32_e32 v190, 0
	v_mov_b32_dpp v184, v191 row_ror:1 row_mask:0xf bank_mask:0xf
	v_mov_b32_dpp v185, v183 row_shr:2 row_mask:0xf bank_mask:0xf
	v_fma_f32 v185, v167, v185, v159
	v_mov_b32_dpp v184, v183 row_shr:1 row_mask:0xf bank_mask:0xf
	v_fmac_f32_e32 v185, v171, v184
	v_fmac_f32_e32 v185, v183, v175
	v_mul_f32_e32 v184, 0xbfb8aa3b, v185
	v_exp_f32_e32 v184, v184
	v_mov_b32_e32 v191, 0
	v_mov_b32_dpp v190, v187 row_ror:1 row_mask:0xf bank_mask:0xf
	v_mov_b32_e32 v193, 0
	v_add_f32_e32 v184, 1.0, v184
	v_mov_b32_dpp v191, v187 row_ror:2 row_mask:0xf bank_mask:0xf
	v_rcp_f32_e32 v184, v184
	v_mov_b32_dpp v190, v179 row_shr:1 row_mask:0xf bank_mask:0xf
	v_mov_b32_dpp v191, v179 row_shr:2 row_mask:0xf bank_mask:0xf
	v_fma_f32 v187, v147, v191, v163
	v_fmac_f32_e32 v187, v151, v190
	v_fmac_f32_e32 v187, v179, v155
	v_mul_f32_e32 v184, v185, v184
	v_mul_f32_e32 v187, v187, v184
	v_or_b32_e32 v184, 16, v210
	v_mad_i64_i32 v[184:185], s[54:55], v184, s77, v[194:195]
	v_lshl_add_u64 v[184:185], v[184:185], 0, v[198:199]
	v_cvt_pk_bf16_f32 v243, v186, v187
	v_mov_b32_e32 v187, 0
	v_mov_b32_e32 v186, 0
	v_mov_b32_dpp v187, v180 row_ror:2 row_mask:0xf bank_mask:0xf
	v_mov_b32_e32 v188, 0
	v_mov_b32_dpp v186, v180 row_ror:1 row_mask:0xf bank_mask:0xf
	v_mov_b32_dpp v187, v140 row_shr:2 row_mask:0xf bank_mask:0xf
	v_fma_f32 v187, v164, v187, v156
	v_mov_b32_dpp v186, v140 row_shr:1 row_mask:0xf bank_mask:0xf
	v_fmac_f32_e32 v187, v168, v186
	v_fmac_f32_e32 v187, v140, v172
	v_mul_f32_e32 v186, 0xbfb8aa3b, v187
	v_exp_f32_e32 v186, v186
	v_mov_b32_e32 v180, 0
	v_mov_b32_dpp v188, v176 row_ror:2 row_mask:0xf bank_mask:0xf
	s_nop 0
	v_mov_b32_dpp v180, v176 row_ror:1 row_mask:0xf bank_mask:0xf
	v_add_f32_e32 v176, 1.0, v186
	v_rcp_f32_e32 v176, v176
	v_mov_b32_dpp v188, v132 row_shr:2 row_mask:0xf bank_mask:0xf
	v_mov_b32_dpp v180, v132 row_shr:1 row_mask:0xf bank_mask:0xf
	v_fma_f32 v186, v144, v188, v160
	v_fmac_f32_e32 v186, v148, v180
	v_fmac_f32_e32 v186, v132, v152
	v_mul_f32_e32 v176, v187, v176
	v_mul_f32_e32 v180, v186, v176
	v_mov_b32_e32 v186, 0
	v_mov_b32_e32 v176, 0
	v_mov_b32_e32 v187, 0
	v_mov_b32_dpp v186, v181 row_ror:2 row_mask:0xf bank_mask:0xf
	v_mov_b32_dpp v176, v181 row_ror:1 row_mask:0xf bank_mask:0xf
	v_mov_b32_e32 v181, 0
	v_mov_b32_dpp v186, v141 row_shr:2 row_mask:0xf bank_mask:0xf
	v_mov_b32_dpp v176, v141 row_shr:1 row_mask:0xf bank_mask:0xf
	v_fma_f32 v186, v165, v186, v157
	v_fmac_f32_e32 v186, v169, v176
	v_fmac_f32_e32 v186, v141, v173
	v_mul_f32_e32 v176, 0xbfb8aa3b, v186
	v_exp_f32_e32 v176, v176
	v_mov_b32_dpp v187, v177 row_ror:2 row_mask:0xf bank_mask:0xf
	v_mov_b32_dpp v181, v177 row_ror:1 row_mask:0xf bank_mask:0xf
	v_add_f32_e32 v176, 1.0, v176
	v_rcp_f32_e32 v176, v176
	v_mov_b32_dpp v187, v133 row_shr:2 row_mask:0xf bank_mask:0xf
	v_mov_b32_dpp v181, v133 row_shr:1 row_mask:0xf bank_mask:0xf
	v_fma_f32 v177, v145, v187, v161
	v_fmac_f32_e32 v177, v149, v181
	v_fmac_f32_e32 v177, v133, v153
	v_mul_f32_e32 v176, v186, v176
	v_mul_f32_e32 v181, v177, v176
	v_mov_b32_e32 v177, 0
	v_mov_b32_e32 v176, 0
	v_mov_b32_e32 v186, 0
	v_mov_b32_dpp v177, v182 row_ror:2 row_mask:0xf bank_mask:0xf
	v_mov_b32_dpp v176, v182 row_ror:1 row_mask:0xf bank_mask:0xf
	v_mov_b32_e32 v182, 0
	v_mov_b32_dpp v177, v142 row_shr:2 row_mask:0xf bank_mask:0xf
	v_mov_b32_dpp v176, v142 row_shr:1 row_mask:0xf bank_mask:0xf
	v_fma_f32 v177, v166, v177, v158
	v_fmac_f32_e32 v177, v170, v176
	v_fmac_f32_e32 v177, v142, v174
	v_mul_f32_e32 v176, 0xbfb8aa3b, v177
	v_exp_f32_e32 v176, v176
	v_mov_b32_dpp v186, v178 row_ror:2 row_mask:0xf bank_mask:0xf
	v_mov_b32_dpp v182, v178 row_ror:1 row_mask:0xf bank_mask:0xf
	v_cvt_pk_bf16_f32 v200, v180, v181
	v_add_f32_e32 v176, 1.0, v176
	v_rcp_f32_e32 v176, v176
	v_mov_b32_dpp v186, v134 row_shr:2 row_mask:0xf bank_mask:0xf
	v_mov_b32_dpp v182, v134 row_shr:1 row_mask:0xf bank_mask:0xf
	v_fma_f32 v178, v146, v186, v162
	v_fmac_f32_e32 v178, v150, v182
	v_fmac_f32_e32 v178, v134, v154
	v_mul_f32_e32 v176, v177, v176
	v_mov_b32_e32 v177, 0
	v_mul_f32_e32 v178, v178, v176
	v_mov_b32_e32 v176, 0
	v_mov_b32_dpp v177, v183 row_ror:2 row_mask:0xf bank_mask:0xf
	v_mov_b32_e32 v182, 0
	v_mov_b32_dpp v176, v183 row_ror:1 row_mask:0xf bank_mask:0xf
	v_mov_b32_dpp v177, v143 row_shr:2 row_mask:0xf bank_mask:0xf
	v_fma_f32 v177, v167, v177, v159
	v_mov_b32_dpp v176, v143 row_shr:1 row_mask:0xf bank_mask:0xf
	v_fmac_f32_e32 v177, v171, v176
	v_fmac_f32_e32 v177, v143, v175
	v_mul_f32_e32 v176, 0xbfb8aa3b, v177
	v_exp_f32_e32 v176, v176
	v_mov_b32_e32 v183, 0
	v_mov_b32_dpp v182, v179 row_ror:1 row_mask:0xf bank_mask:0xf
	v_add_f32_e32 v176, 1.0, v176
	v_mov_b32_dpp v183, v179 row_ror:2 row_mask:0xf bank_mask:0xf
	v_rcp_f32_e32 v176, v176
	v_mov_b32_dpp v182, v135 row_shr:1 row_mask:0xf bank_mask:0xf
	v_mov_b32_dpp v183, v135 row_shr:2 row_mask:0xf bank_mask:0xf
	v_fma_f32 v179, v147, v183, v163
	v_fmac_f32_e32 v179, v151, v182
	v_fmac_f32_e32 v179, v135, v155
	v_mul_f32_e32 v176, v177, v176
	v_mul_f32_e32 v179, v179, v176
	v_or_b32_e32 v176, 32, v210
	v_mad_i64_i32 v[176:177], s[54:55], v176, s77, v[194:195]
	v_lshl_add_u64 v[176:177], v[176:177], 0, v[198:199]
	v_cvt_pk_bf16_f32 v201, v178, v179
	v_mov_b32_e32 v179, 0
	v_mov_b32_e32 v178, 0
	v_mov_b32_dpp v179, v140 row_ror:2 row_mask:0xf bank_mask:0xf
	s_nop 0
	v_mov_b32_dpp v178, v140 row_ror:1 row_mask:0xf bank_mask:0xf
	v_mov_b32_dpp v179, v136 row_shr:2 row_mask:0xf bank_mask:0xf
	v_fma_f32 v179, v164, v179, v156
	v_mov_b32_dpp v178, v136 row_shr:1 row_mask:0xf bank_mask:0xf
	v_fmac_f32_e32 v179, v168, v178
	v_fmac_f32_e32 v179, v136, v172
	v_mul_f32_e32 v136, 0xbfb8aa3b, v179
	v_exp_f32_e32 v136, v136
	v_mov_b32_e32 v140, 0
	v_mov_b32_e32 v178, 0
	s_nop 0
	v_mov_b32_dpp v140, v132 row_ror:1 row_mask:0xf bank_mask:0xf
	v_mov_b32_dpp v178, v132 row_ror:2 row_mask:0xf bank_mask:0xf
	v_add_f32_e32 v132, 1.0, v136
	v_rcp_f32_e32 v132, v132
	v_mov_b32_dpp v178, v128 row_shr:2 row_mask:0xf bank_mask:0xf
	v_mov_b32_dpp v140, v128 row_shr:1 row_mask:0xf bank_mask:0xf
	v_fma_f32 v136, v144, v178, v160
	v_fmac_f32_e32 v136, v148, v140
	v_fmac_f32_e32 v136, v128, v152
	v_mul_f32_e32 v128, v179, v132
	v_mul_f32_e32 v132, v136, v128
	v_mov_b32_e32 v136, 0
	v_mov_b32_e32 v128, 0
	v_mov_b32_e32 v140, 0
	v_mov_b32_dpp v136, v141 row_ror:2 row_mask:0xf bank_mask:0xf
	v_mov_b32_dpp v128, v141 row_ror:1 row_mask:0xf bank_mask:0xf
	v_mov_b32_dpp v140, v133 row_ror:1 row_mask:0xf bank_mask:0xf
	v_mov_b32_dpp v136, v137 row_shr:2 row_mask:0xf bank_mask:0xf
	v_mov_b32_dpp v128, v137 row_shr:1 row_mask:0xf bank_mask:0xf
	v_fma_f32 v136, v165, v136, v157
	v_fmac_f32_e32 v136, v169, v128
	v_fmac_f32_e32 v136, v137, v173
	v_mul_f32_e32 v128, 0xbfb8aa3b, v136
	v_exp_f32_e32 v128, v128
	v_mov_b32_e32 v137, 0
	v_mov_b32_dpp v140, v129 row_shr:1 row_mask:0xf bank_mask:0xf
	v_add_f32_e32 v128, 1.0, v128
	v_mov_b32_dpp v137, v133 row_ror:2 row_mask:0xf bank_mask:0xf
	v_rcp_f32_e32 v128, v128
	s_nop 0
	v_mov_b32_dpp v137, v129 row_shr:2 row_mask:0xf bank_mask:0xf
	v_fma_f32 v133, v145, v137, v161
	v_fmac_f32_e32 v133, v149, v140
	v_fmac_f32_e32 v133, v129, v153
	v_mul_f32_e32 v128, v136, v128
	v_mov_b32_e32 v129, 0
	v_mul_f32_e32 v133, v133, v128
	v_mov_b32_e32 v128, 0
	v_mov_b32_dpp v129, v142 row_ror:2 row_mask:0xf bank_mask:0xf
	v_mov_b32_e32 v137, 0
	v_mov_b32_dpp v128, v142 row_ror:1 row_mask:0xf bank_mask:0xf
	v_mov_b32_dpp v129, v138 row_shr:2 row_mask:0xf bank_mask:0xf
	v_fma_f32 v129, v166, v129, v158
	v_mov_b32_dpp v128, v138 row_shr:1 row_mask:0xf bank_mask:0xf
	v_fmac_f32_e32 v129, v170, v128
	v_fmac_f32_e32 v129, v138, v174
	v_mul_f32_e32 v128, 0xbfb8aa3b, v129
	v_exp_f32_e32 v128, v128
	v_mov_b32_e32 v136, 0
	v_mov_b32_dpp v137, v134 row_ror:2 row_mask:0xf bank_mask:0xf
	v_add_f32_e32 v128, 1.0, v128
	v_rcp_f32_e32 v128, v128
	v_mov_b32_dpp v136, v134 row_ror:1 row_mask:0xf bank_mask:0xf
	v_mov_b32_dpp v137, v130 row_shr:2 row_mask:0xf bank_mask:0xf
	v_fma_f32 v134, v146, v137, v162
	v_mov_b32_dpp v136, v130 row_shr:1 row_mask:0xf bank_mask:0xf
	v_fmac_f32_e32 v134, v150, v136
	v_fmac_f32_e32 v134, v130, v154
	v_mul_f32_e32 v128, v129, v128
	v_mov_b32_e32 v129, 0
	v_mul_f32_e32 v130, v134, v128
	v_mov_b32_e32 v128, 0
	v_mov_b32_dpp v129, v143 row_ror:2 row_mask:0xf bank_mask:0xf
	v_mov_b32_e32 v136, 0
	v_mov_b32_dpp v128, v143 row_ror:1 row_mask:0xf bank_mask:0xf
	v_mov_b32_dpp v129, v139 row_shr:2 row_mask:0xf bank_mask:0xf
	v_fma_f32 v129, v167, v129, v159
	v_mov_b32_dpp v128, v139 row_shr:1 row_mask:0xf bank_mask:0xf
	v_fmac_f32_e32 v129, v171, v128
	v_fmac_f32_e32 v129, v139, v175
	v_mul_f32_e32 v128, 0xbfb8aa3b, v129
	v_exp_f32_e32 v128, v128
	v_mov_b32_e32 v134, 0
	v_mov_b32_dpp v136, v135 row_ror:2 row_mask:0xf bank_mask:0xf
	v_add_f32_e32 v128, 1.0, v128
	v_rcp_f32_e32 v128, v128
	v_mov_b32_dpp v134, v135 row_ror:1 row_mask:0xf bank_mask:0xf
	v_mov_b32_dpp v136, v131 row_shr:2 row_mask:0xf bank_mask:0xf
	v_fma_f32 v135, v147, v136, v163
	v_mov_b32_dpp v134, v131 row_shr:1 row_mask:0xf bank_mask:0xf
	v_fmac_f32_e32 v135, v151, v134
	v_fmac_f32_e32 v135, v131, v155
	v_mul_f32_e32 v128, v129, v128
	v_mul_f32_e32 v131, v135, v128
	v_or_b32_e32 v128, 48, v210
	v_mad_i64_i32 v[128:129], s[54:55], v128, s77, v[194:195]
	v_lshl_add_u64 v[134:135], v[128:129], 0, v[198:199]
	v_cvt_pk_bf16_f32 v226, v132, v133
	v_cvt_pk_bf16_f32 v227, v130, v131
	v_mov_b32_e32 v194, 0
	v_mov_b32_e32 v195, 0
	v_mov_b32_e32 v130, 0
	v_mov_b32_e32 v131, 0
	v_mov_b32_e32 v132, 0
	v_mov_b32_e32 v133, 0
	s_and_saveexec_b64 s[54:55], s[4:5]
	s_cbranch_execz .LBB0_717
	ds_read_b128 v[192:195], v233
	ds_read_b128 v[130:133], v232
.LBB0_717:
	s_or_b64 exec, exec, s[54:55]
	v_mov_b32_e32 v137, 0
	v_mov_b32_e32 v136, 0
	v_mov_b32_e32 v138, 0
	s_waitcnt lgkmcnt(1)
	v_mov_b32_dpp v137, v192 row_ror:2 row_mask:0xf bank_mask:0xf
	v_mov_b32_dpp v136, v192 row_ror:1 row_mask:0xf bank_mask:0xf
	v_mov_b32_e32 v139, 0
	v_mov_b32_dpp v137, v124 row_shr:2 row_mask:0xf bank_mask:0xf
	v_mov_b32_dpp v136, v124 row_shr:1 row_mask:0xf bank_mask:0xf
	v_fma_f32 v137, v164, v137, v156
	v_fmac_f32_e32 v137, v168, v136
	v_fmac_f32_e32 v137, v124, v172
	v_mul_f32_e32 v136, 0xbfb8aa3b, v137
	v_exp_f32_e32 v136, v136
	s_waitcnt lgkmcnt(0)
	v_mov_b32_dpp v138, v130 row_ror:1 row_mask:0xf bank_mask:0xf
	v_mov_b32_dpp v139, v130 row_ror:2 row_mask:0xf bank_mask:0xf
	v_add_u32_e32 v129, 0x80, v210
	v_add_f32_e32 v130, 1.0, v136
	v_rcp_f32_e32 v130, v130
	v_mov_b32_dpp v139, v120 row_shr:2 row_mask:0xf bank_mask:0xf
	v_mov_b32_dpp v138, v120 row_shr:1 row_mask:0xf bank_mask:0xf
	v_fma_f32 v136, v144, v139, v160
	v_fmac_f32_e32 v136, v148, v138
	v_fmac_f32_e32 v136, v120, v152
	v_mul_f32_e32 v130, v137, v130
	v_mov_b32_e32 v137, 0
	v_mul_f32_e32 v136, v136, v130
	v_mov_b32_e32 v130, 0
	v_mov_b32_dpp v137, v193 row_ror:2 row_mask:0xf bank_mask:0xf
	v_mov_b32_e32 v139, 0
	v_mov_b32_dpp v130, v193 row_ror:1 row_mask:0xf bank_mask:0xf
	v_mov_b32_dpp v137, v125 row_shr:2 row_mask:0xf bank_mask:0xf
	v_fma_f32 v137, v165, v137, v157
	v_mov_b32_dpp v130, v125 row_shr:1 row_mask:0xf bank_mask:0xf
	v_fmac_f32_e32 v137, v169, v130
	v_fmac_f32_e32 v137, v125, v173
	v_mul_f32_e32 v130, 0xbfb8aa3b, v137
	v_exp_f32_e32 v130, v130
	v_mov_b32_e32 v138, 0
	v_mov_b32_dpp v139, v131 row_ror:2 row_mask:0xf bank_mask:0xf
	v_mov_b32_e32 v128, 0
	v_add_f32_e32 v130, 1.0, v130
	v_rcp_f32_e32 v130, v130
	v_mov_b32_dpp v138, v131 row_ror:1 row_mask:0xf bank_mask:0xf
	v_mov_b32_dpp v139, v121 row_shr:2 row_mask:0xf bank_mask:0xf
	v_fma_f32 v131, v145, v139, v161
	v_mov_b32_dpp v138, v121 row_shr:1 row_mask:0xf bank_mask:0xf
	v_fmac_f32_e32 v131, v149, v138
	v_fmac_f32_e32 v131, v121, v153
	v_mul_f32_e32 v130, v137, v130
	v_mul_f32_e32 v137, v131, v130
	v_mov_b32_e32 v131, 0
	v_mov_b32_e32 v130, 0
	v_mov_b32_e32 v139, 0
	v_mov_b32_dpp v131, v194 row_ror:2 row_mask:0xf bank_mask:0xf
	v_mov_b32_dpp v130, v194 row_ror:1 row_mask:0xf bank_mask:0xf
	v_mov_b32_e32 v138, 0
	v_mov_b32_dpp v131, v126 row_shr:2 row_mask:0xf bank_mask:0xf
	v_mov_b32_dpp v130, v126 row_shr:1 row_mask:0xf bank_mask:0xf
	v_fma_f32 v131, v166, v131, v158
	v_fmac_f32_e32 v131, v170, v130
	v_fmac_f32_e32 v131, v126, v174
	v_mul_f32_e32 v130, 0xbfb8aa3b, v131
	v_exp_f32_e32 v130, v130
	v_mov_b32_dpp v139, v132 row_ror:2 row_mask:0xf bank_mask:0xf
	v_mov_b32_dpp v138, v132 row_ror:1 row_mask:0xf bank_mask:0xf
	v_add_f32_e32 v130, 1.0, v130
	v_rcp_f32_e32 v130, v130
	v_mov_b32_dpp v139, v122 row_shr:2 row_mask:0xf bank_mask:0xf
	v_mov_b32_dpp v138, v122 row_shr:1 row_mask:0xf bank_mask:0xf
	v_fma_f32 v132, v146, v139, v162
	v_fmac_f32_e32 v132, v150, v138
	v_fmac_f32_e32 v132, v122, v154
	v_mul_f32_e32 v130, v131, v130
	v_mov_b32_e32 v131, 0
	v_mul_f32_e32 v138, v132, v130
	v_mov_b32_e32 v130, 0
	v_mov_b32_dpp v131, v195 row_ror:2 row_mask:0xf bank_mask:0xf
	v_mov_b32_e32 v139, 0
	v_mov_b32_dpp v130, v195 row_ror:1 row_mask:0xf bank_mask:0xf
	v_mov_b32_dpp v131, v127 row_shr:2 row_mask:0xf bank_mask:0xf
	v_fma_f32 v131, v167, v131, v159
	v_mov_b32_dpp v130, v127 row_shr:1 row_mask:0xf bank_mask:0xf
	v_fmac_f32_e32 v131, v171, v130
	v_fmac_f32_e32 v131, v127, v175
	v_mul_f32_e32 v130, 0xbfb8aa3b, v131
	v_exp_f32_e32 v130, v130
	v_mov_b32_e32 v132, 0
	v_mov_b32_dpp v139, v133 row_ror:2 row_mask:0xf bank_mask:0xf
	v_add_f32_e32 v130, 1.0, v130
	v_rcp_f32_e32 v130, v130
	v_mov_b32_dpp v132, v133 row_ror:1 row_mask:0xf bank_mask:0xf
	v_mov_b32_dpp v139, v123 row_shr:2 row_mask:0xf bank_mask:0xf
	v_fma_f32 v133, v147, v139, v163
	v_mov_b32_dpp v132, v123 row_shr:1 row_mask:0xf bank_mask:0xf
	v_fmac_f32_e32 v133, v151, v132
	v_fmac_f32_e32 v133, v123, v155
	v_mul_f32_e32 v130, v131, v130
	v_mul_f32_e32 v139, v133, v130
	v_mov_b64_e32 v[130:131], s[12:13]
	v_mad_i64_i32 v[132:133], s[54:55], v129, s77, v[130:131]
	v_lshl_add_u64 v[132:133], v[132:133], 0, v[198:199]
	v_cvt_pk_bf16_f32 v186, v136, v137
	v_cvt_pk_bf16_f32 v187, v138, v139
	v_mov_b32_e32 v136, 0
	v_mov_b32_e32 v129, 0
	v_mov_b32_dpp v136, v124 row_ror:2 row_mask:0xf bank_mask:0xf
	v_mov_b32_e32 v137, 0
	v_mov_b32_dpp v129, v124 row_ror:1 row_mask:0xf bank_mask:0xf
	v_mov_b32_dpp v136, v116 row_shr:2 row_mask:0xf bank_mask:0xf
	v_fma_f32 v136, v164, v136, v156
	v_mov_b32_dpp v129, v116 row_shr:1 row_mask:0xf bank_mask:0xf
	v_fmac_f32_e32 v136, v168, v129
	v_fmac_f32_e32 v136, v116, v172
	v_mul_f32_e32 v129, 0xbfb8aa3b, v136
	v_exp_f32_e32 v129, v129
	v_mov_b32_e32 v124, 0
	v_mov_b32_dpp v137, v120 row_ror:2 row_mask:0xf bank_mask:0xf
	s_nop 0
	v_mov_b32_dpp v124, v120 row_ror:1 row_mask:0xf bank_mask:0xf
	v_add_f32_e32 v120, 1.0, v129
	v_rcp_f32_e32 v120, v120
	v_mov_b32_dpp v137, v112 row_shr:2 row_mask:0xf bank_mask:0xf
	v_mov_b32_dpp v124, v112 row_shr:1 row_mask:0xf bank_mask:0xf
	v_fma_f32 v129, v144, v137, v160
	v_fmac_f32_e32 v129, v148, v124
	v_fmac_f32_e32 v129, v112, v152
	v_mul_f32_e32 v120, v136, v120
	v_mul_f32_e32 v124, v129, v120
	v_mov_b32_e32 v129, 0
	v_mov_b32_e32 v120, 0
	v_mov_b32_e32 v136, 0
	v_mov_b32_dpp v129, v125 row_ror:2 row_mask:0xf bank_mask:0xf
	v_mov_b32_dpp v120, v125 row_ror:1 row_mask:0xf bank_mask:0xf
	v_mov_b32_e32 v125, 0
	v_mov_b32_dpp v129, v117 row_shr:2 row_mask:0xf bank_mask:0xf
	v_mov_b32_dpp v120, v117 row_shr:1 row_mask:0xf bank_mask:0xf
	v_fma_f32 v129, v165, v129, v157
	v_fmac_f32_e32 v129, v169, v120
	v_fmac_f32_e32 v129, v117, v173
	v_mul_f32_e32 v120, 0xbfb8aa3b, v129
	v_exp_f32_e32 v120, v120
	v_mov_b32_dpp v136, v121 row_ror:2 row_mask:0xf bank_mask:0xf
	v_mov_b32_dpp v125, v121 row_ror:1 row_mask:0xf bank_mask:0xf
	v_add_f32_e32 v120, 1.0, v120
	v_rcp_f32_e32 v120, v120
	v_mov_b32_dpp v136, v113 row_shr:2 row_mask:0xf bank_mask:0xf
	v_mov_b32_dpp v125, v113 row_shr:1 row_mask:0xf bank_mask:0xf
	v_fma_f32 v121, v145, v136, v161
	v_fmac_f32_e32 v121, v149, v125
	v_fmac_f32_e32 v121, v113, v153
	v_mul_f32_e32 v120, v129, v120
	v_mul_f32_e32 v125, v121, v120
	v_mov_b32_e32 v121, 0
	v_mov_b32_e32 v120, 0
	v_mov_b32_e32 v129, 0
	v_mov_b32_dpp v121, v126 row_ror:2 row_mask:0xf bank_mask:0xf
	v_mov_b32_dpp v120, v126 row_ror:1 row_mask:0xf bank_mask:0xf
	v_mov_b32_e32 v126, 0
	v_mov_b32_dpp v121, v118 row_shr:2 row_mask:0xf bank_mask:0xf
	v_mov_b32_dpp v120, v118 row_shr:1 row_mask:0xf bank_mask:0xf
	v_fma_f32 v121, v166, v121, v158
	v_fmac_f32_e32 v121, v170, v120
	v_fmac_f32_e32 v121, v118, v174
	v_mul_f32_e32 v120, 0xbfb8aa3b, v121
	v_exp_f32_e32 v120, v120
	v_mov_b32_dpp v129, v122 row_ror:2 row_mask:0xf bank_mask:0xf
	v_mov_b32_dpp v126, v122 row_ror:1 row_mask:0xf bank_mask:0xf
	v_cvt_pk_bf16_f32 v188, v124, v125
	v_add_f32_e32 v120, 1.0, v120
	v_rcp_f32_e32 v120, v120
	v_mov_b32_dpp v129, v114 row_shr:2 row_mask:0xf bank_mask:0xf
	v_mov_b32_dpp v126, v114 row_shr:1 row_mask:0xf bank_mask:0xf
	v_fma_f32 v122, v146, v129, v162
	v_fmac_f32_e32 v122, v150, v126
	v_fmac_f32_e32 v122, v114, v154
	v_mul_f32_e32 v120, v121, v120
	v_mov_b32_e32 v121, 0
	v_mul_f32_e32 v122, v122, v120
	v_mov_b32_e32 v120, 0
	v_mov_b32_dpp v121, v127 row_ror:2 row_mask:0xf bank_mask:0xf
	v_mov_b32_e32 v126, 0
	v_mov_b32_dpp v120, v127 row_ror:1 row_mask:0xf bank_mask:0xf
	v_mov_b32_dpp v121, v119 row_shr:2 row_mask:0xf bank_mask:0xf
	v_fma_f32 v121, v167, v121, v159
	v_mov_b32_dpp v120, v119 row_shr:1 row_mask:0xf bank_mask:0xf
	v_fmac_f32_e32 v121, v171, v120
	v_fmac_f32_e32 v121, v119, v175
	v_mul_f32_e32 v120, 0xbfb8aa3b, v121
	v_exp_f32_e32 v120, v120
	v_mov_b32_e32 v127, 0
	v_mov_b32_dpp v126, v123 row_ror:1 row_mask:0xf bank_mask:0xf
	v_add_f32_e32 v120, 1.0, v120
	v_mov_b32_dpp v127, v123 row_ror:2 row_mask:0xf bank_mask:0xf
	v_rcp_f32_e32 v120, v120
	v_mov_b32_dpp v126, v115 row_shr:1 row_mask:0xf bank_mask:0xf
	v_mov_b32_dpp v127, v115 row_shr:2 row_mask:0xf bank_mask:0xf
	v_fma_f32 v123, v147, v127, v163
	v_fmac_f32_e32 v123, v151, v126
	v_fmac_f32_e32 v123, v115, v155
	v_mul_f32_e32 v120, v121, v120
	v_mul_f32_e32 v123, v123, v120
	v_add_u32_e32 v120, 0x90, v210
	v_mad_i64_i32 v[120:121], s[54:55], v120, s77, v[130:131]
	v_lshl_add_u64 v[120:121], v[120:121], 0, v[198:199]
	v_cvt_pk_bf16_f32 v189, v122, v123
	v_mov_b32_e32 v123, 0
	v_mov_b32_e32 v122, 0
	v_mov_b32_dpp v123, v116 row_ror:2 row_mask:0xf bank_mask:0xf
	v_mov_b32_e32 v124, 0
	v_mov_b32_dpp v122, v116 row_ror:1 row_mask:0xf bank_mask:0xf
	v_mov_b32_dpp v123, v108 row_shr:2 row_mask:0xf bank_mask:0xf
	v_fma_f32 v123, v164, v123, v156
	v_mov_b32_dpp v122, v108 row_shr:1 row_mask:0xf bank_mask:0xf
	v_fmac_f32_e32 v123, v168, v122
	v_fmac_f32_e32 v123, v108, v172
	v_mul_f32_e32 v122, 0xbfb8aa3b, v123
	v_exp_f32_e32 v122, v122
	v_mov_b32_e32 v116, 0
	v_mov_b32_dpp v124, v112 row_ror:2 row_mask:0xf bank_mask:0xf
	s_nop 0
	v_mov_b32_dpp v116, v112 row_ror:1 row_mask:0xf bank_mask:0xf
	v_add_f32_e32 v112, 1.0, v122
	v_rcp_f32_e32 v112, v112
	v_mov_b32_dpp v124, v100 row_shr:2 row_mask:0xf bank_mask:0xf
	v_mov_b32_dpp v116, v100 row_shr:1 row_mask:0xf bank_mask:0xf
	v_fma_f32 v122, v144, v124, v160
	v_fmac_f32_e32 v122, v148, v116
	v_fmac_f32_e32 v122, v100, v152
	v_mul_f32_e32 v112, v123, v112
	v_mul_f32_e32 v116, v122, v112
	v_mov_b32_e32 v122, 0
	v_mov_b32_e32 v112, 0
	v_mov_b32_e32 v123, 0
	v_mov_b32_dpp v122, v117 row_ror:2 row_mask:0xf bank_mask:0xf
	v_mov_b32_dpp v112, v117 row_ror:1 row_mask:0xf bank_mask:0xf
	v_mov_b32_e32 v117, 0
	v_mov_b32_dpp v122, v109 row_shr:2 row_mask:0xf bank_mask:0xf
	v_mov_b32_dpp v112, v109 row_shr:1 row_mask:0xf bank_mask:0xf
	v_fma_f32 v122, v165, v122, v157
	v_fmac_f32_e32 v122, v169, v112
	v_fmac_f32_e32 v122, v109, v173
	v_mul_f32_e32 v112, 0xbfb8aa3b, v122
	v_exp_f32_e32 v112, v112
	v_mov_b32_dpp v123, v113 row_ror:2 row_mask:0xf bank_mask:0xf
	v_mov_b32_dpp v117, v113 row_ror:1 row_mask:0xf bank_mask:0xf
	v_add_f32_e32 v112, 1.0, v112
	v_rcp_f32_e32 v112, v112
	v_mov_b32_dpp v123, v101 row_shr:2 row_mask:0xf bank_mask:0xf
	v_mov_b32_dpp v117, v101 row_shr:1 row_mask:0xf bank_mask:0xf
	v_fma_f32 v113, v145, v123, v161
	v_fmac_f32_e32 v113, v149, v117
	v_fmac_f32_e32 v113, v101, v153
	v_mul_f32_e32 v112, v122, v112
	v_mul_f32_e32 v117, v113, v112
	v_mov_b32_e32 v113, 0
	v_mov_b32_e32 v112, 0
	v_mov_b32_e32 v122, 0
	v_mov_b32_dpp v113, v118 row_ror:2 row_mask:0xf bank_mask:0xf
	v_mov_b32_dpp v112, v118 row_ror:1 row_mask:0xf bank_mask:0xf
	v_mov_b32_e32 v118, 0
	v_mov_b32_dpp v113, v110 row_shr:2 row_mask:0xf bank_mask:0xf
	v_mov_b32_dpp v112, v110 row_shr:1 row_mask:0xf bank_mask:0xf
	v_fma_f32 v113, v166, v113, v158
	v_fmac_f32_e32 v113, v170, v112
	v_fmac_f32_e32 v113, v110, v174
	v_mul_f32_e32 v112, 0xbfb8aa3b, v113
	v_exp_f32_e32 v112, v112
	v_mov_b32_dpp v122, v114 row_ror:2 row_mask:0xf bank_mask:0xf
	v_mov_b32_dpp v118, v114 row_ror:1 row_mask:0xf bank_mask:0xf
	v_cvt_pk_bf16_f32 v190, v116, v117
	v_add_f32_e32 v112, 1.0, v112
	v_rcp_f32_e32 v112, v112
	v_mov_b32_dpp v122, v102 row_shr:2 row_mask:0xf bank_mask:0xf
	v_mov_b32_dpp v118, v102 row_shr:1 row_mask:0xf bank_mask:0xf
	v_fma_f32 v114, v146, v122, v162
	v_fmac_f32_e32 v114, v150, v118
	v_fmac_f32_e32 v114, v102, v154
	v_mul_f32_e32 v112, v113, v112
	v_mov_b32_e32 v113, 0
	v_mul_f32_e32 v114, v114, v112
	v_mov_b32_e32 v112, 0
	v_mov_b32_dpp v113, v119 row_ror:2 row_mask:0xf bank_mask:0xf
	v_mov_b32_e32 v118, 0
	v_mov_b32_dpp v112, v119 row_ror:1 row_mask:0xf bank_mask:0xf
	v_mov_b32_dpp v113, v111 row_shr:2 row_mask:0xf bank_mask:0xf
	v_fma_f32 v113, v167, v113, v159
	v_mov_b32_dpp v112, v111 row_shr:1 row_mask:0xf bank_mask:0xf
	v_fmac_f32_e32 v113, v171, v112
	v_fmac_f32_e32 v113, v111, v175
	v_mul_f32_e32 v112, 0xbfb8aa3b, v113
	v_exp_f32_e32 v112, v112
	v_mov_b32_e32 v119, 0
	v_mov_b32_dpp v118, v115 row_ror:1 row_mask:0xf bank_mask:0xf
	v_add_f32_e32 v112, 1.0, v112
	v_mov_b32_dpp v119, v115 row_ror:2 row_mask:0xf bank_mask:0xf
	v_rcp_f32_e32 v112, v112
	v_mov_b32_dpp v118, v103 row_shr:1 row_mask:0xf bank_mask:0xf
	v_mov_b32_dpp v119, v103 row_shr:2 row_mask:0xf bank_mask:0xf
	v_fma_f32 v115, v147, v119, v163
	v_fmac_f32_e32 v115, v151, v118
	v_fmac_f32_e32 v115, v103, v155
	v_mul_f32_e32 v112, v113, v112
	v_mul_f32_e32 v115, v115, v112
	v_add_u32_e32 v112, 0xa0, v210
	v_mad_i64_i32 v[112:113], s[54:55], v112, s77, v[130:131]
	v_lshl_add_u64 v[112:113], v[112:113], 0, v[198:199]
	v_cvt_pk_bf16_f32 v191, v114, v115
	v_mov_b32_e32 v115, 0
	v_mov_b32_e32 v114, 0
	v_mov_b32_dpp v115, v108 row_ror:2 row_mask:0xf bank_mask:0xf
	s_nop 0
	v_mov_b32_dpp v114, v108 row_ror:1 row_mask:0xf bank_mask:0xf
	v_mov_b32_dpp v115, v104 row_shr:2 row_mask:0xf bank_mask:0xf
	v_fma_f32 v115, v164, v115, v156
	v_mov_b32_dpp v114, v104 row_shr:1 row_mask:0xf bank_mask:0xf
	v_fmac_f32_e32 v115, v168, v114
	v_fmac_f32_e32 v115, v104, v172
	v_mul_f32_e32 v104, 0xbfb8aa3b, v115
	v_exp_f32_e32 v104, v104
	v_mov_b32_e32 v108, 0
	v_mov_b32_e32 v114, 0
	s_nop 0
	v_mov_b32_dpp v108, v100 row_ror:1 row_mask:0xf bank_mask:0xf
	v_mov_b32_dpp v114, v100 row_ror:2 row_mask:0xf bank_mask:0xf
	v_add_f32_e32 v100, 1.0, v104
	v_rcp_f32_e32 v100, v100
	v_mov_b32_dpp v114, v96 row_shr:2 row_mask:0xf bank_mask:0xf
	v_mov_b32_dpp v108, v96 row_shr:1 row_mask:0xf bank_mask:0xf
	v_fma_f32 v104, v144, v114, v160
	v_fmac_f32_e32 v104, v148, v108
	v_fmac_f32_e32 v104, v96, v152
	v_mul_f32_e32 v96, v115, v100
	v_mul_f32_e32 v100, v104, v96
	v_mov_b32_e32 v104, 0
	v_mov_b32_e32 v96, 0
	v_mov_b32_e32 v108, 0
	v_mov_b32_dpp v104, v109 row_ror:2 row_mask:0xf bank_mask:0xf
	v_mov_b32_dpp v96, v109 row_ror:1 row_mask:0xf bank_mask:0xf
	v_mov_b32_dpp v108, v101 row_ror:1 row_mask:0xf bank_mask:0xf
	v_mov_b32_dpp v104, v105 row_shr:2 row_mask:0xf bank_mask:0xf
	v_mov_b32_dpp v96, v105 row_shr:1 row_mask:0xf bank_mask:0xf
	v_fma_f32 v104, v165, v104, v157
	v_fmac_f32_e32 v104, v169, v96
	v_fmac_f32_e32 v104, v105, v173
	v_mul_f32_e32 v96, 0xbfb8aa3b, v104
	v_exp_f32_e32 v96, v96
	v_mov_b32_e32 v105, 0
	v_mov_b32_dpp v108, v97 row_shr:1 row_mask:0xf bank_mask:0xf
	v_add_f32_e32 v96, 1.0, v96
	v_mov_b32_dpp v105, v101 row_ror:2 row_mask:0xf bank_mask:0xf
	v_rcp_f32_e32 v96, v96
	s_nop 0
	v_mov_b32_dpp v105, v97 row_shr:2 row_mask:0xf bank_mask:0xf
	v_fma_f32 v101, v145, v105, v161
	v_fmac_f32_e32 v101, v149, v108
	v_fmac_f32_e32 v101, v97, v153
	v_mul_f32_e32 v96, v104, v96
	v_mov_b32_e32 v97, 0
	v_mul_f32_e32 v101, v101, v96
	v_mov_b32_e32 v96, 0
	v_mov_b32_dpp v97, v110 row_ror:2 row_mask:0xf bank_mask:0xf
	v_mov_b32_e32 v105, 0
	v_mov_b32_dpp v96, v110 row_ror:1 row_mask:0xf bank_mask:0xf
	v_mov_b32_dpp v97, v106 row_shr:2 row_mask:0xf bank_mask:0xf
	v_fma_f32 v97, v166, v97, v158
	v_mov_b32_dpp v96, v106 row_shr:1 row_mask:0xf bank_mask:0xf
	v_fmac_f32_e32 v97, v170, v96
	v_fmac_f32_e32 v97, v106, v174
	v_mul_f32_e32 v96, 0xbfb8aa3b, v97
	v_exp_f32_e32 v96, v96
	v_mov_b32_e32 v104, 0
	v_mov_b32_dpp v105, v102 row_ror:2 row_mask:0xf bank_mask:0xf
	v_add_f32_e32 v96, 1.0, v96
	v_rcp_f32_e32 v96, v96
	v_mov_b32_dpp v104, v102 row_ror:1 row_mask:0xf bank_mask:0xf
	v_mov_b32_dpp v105, v98 row_shr:2 row_mask:0xf bank_mask:0xf
	v_fma_f32 v102, v146, v105, v162
	v_mov_b32_dpp v104, v98 row_shr:1 row_mask:0xf bank_mask:0xf
	v_fmac_f32_e32 v102, v150, v104
	v_fmac_f32_e32 v102, v98, v154
	v_mul_f32_e32 v96, v97, v96
	v_mov_b32_e32 v97, 0
	v_mul_f32_e32 v98, v102, v96
	v_mov_b32_e32 v96, 0
	v_mov_b32_dpp v97, v111 row_ror:2 row_mask:0xf bank_mask:0xf
	v_mov_b32_e32 v102, 0
	v_mov_b32_dpp v96, v111 row_ror:1 row_mask:0xf bank_mask:0xf
	v_mov_b32_dpp v97, v107 row_shr:2 row_mask:0xf bank_mask:0xf
	v_fmac_f32_e32 v159, v167, v97
	v_mov_b32_dpp v96, v107 row_shr:1 row_mask:0xf bank_mask:0xf
	v_fmac_f32_e32 v159, v171, v96
	v_fmac_f32_e32 v159, v107, v175
	v_mul_f32_e32 v96, 0xbfb8aa3b, v159
	v_exp_f32_e32 v96, v96
	v_mov_b32_e32 v97, 0
	v_mov_b32_dpp v102, v103 row_ror:1 row_mask:0xf bank_mask:0xf
	v_add_f32_e32 v96, 1.0, v96
	v_mov_b32_dpp v97, v103 row_ror:2 row_mask:0xf bank_mask:0xf
	v_rcp_f32_e32 v96, v96
	v_mov_b32_dpp v102, v99 row_shr:1 row_mask:0xf bank_mask:0xf
	v_mov_b32_dpp v97, v99 row_shr:2 row_mask:0xf bank_mask:0xf
	v_fmac_f32_e32 v163, v147, v97
	v_fmac_f32_e32 v163, v151, v102
	v_fmac_f32_e32 v163, v99, v155
	v_mul_f32_e32 v96, v159, v96
	v_mul_f32_e32 v99, v163, v96
	v_add_u32_e32 v96, 0xb0, v210
	v_mad_i64_i32 v[96:97], s[54:55], v96, s77, v[130:131]
	v_lshl_add_u64 v[104:105], v[96:97], 0, v[198:199]
	v_cvt_pk_bf16_f32 v192, v100, v101
	v_cvt_pk_bf16_f32 v193, v98, v99
	v_mov_b32_e32 v100, 0
	v_mov_b32_e32 v101, 0
	v_mov_b32_e32 v102, 0
	v_mov_b32_e32 v103, 0
	v_mov_b32_e32 v96, 0
	v_mov_b32_e32 v97, 0
	v_mov_b32_e32 v98, 0
	v_mov_b32_e32 v99, 0
	s_and_saveexec_b64 s[54:55], s[24:25]
	s_cbranch_execz .LBB0_719
	ds_read_b128 v[100:103], v235
	ds_read_b128 v[96:99], v234
.LBB0_719:
	s_or_b64 exec, exec, s[54:55]
	v_mov_b32_e32 v107, 0
	v_mov_b32_e32 v106, 0
	v_mov_b32_e32 v108, 0
	s_waitcnt lgkmcnt(1)
	v_mov_b32_dpp v107, v100 row_ror:2 row_mask:0xf bank_mask:0xf
	v_mov_b32_dpp v106, v100 row_ror:1 row_mask:0xf bank_mask:0xf
	v_mov_b32_e32 v100, 0
	v_mov_b32_dpp v107, v92 row_shr:2 row_mask:0xf bank_mask:0xf
	v_mov_b32_dpp v106, v92 row_shr:1 row_mask:0xf bank_mask:0xf
	v_fma_f32 v107, v68, v107, v60
	v_fmac_f32_e32 v107, v72, v106
	v_fmac_f32_e32 v107, v92, v76
	v_mul_f32_e32 v106, 0xbfb8aa3b, v107
	v_exp_f32_e32 v106, v106
	s_waitcnt lgkmcnt(0)
	v_mov_b32_dpp v100, v96 row_ror:1 row_mask:0xf bank_mask:0xf
	v_mov_b32_dpp v108, v96 row_ror:2 row_mask:0xf bank_mask:0xf
	v_mov_b32_e32 v129, 0
	v_add_f32_e32 v96, 1.0, v106
	v_rcp_f32_e32 v96, v96
	v_mov_b32_dpp v108, v88 row_shr:2 row_mask:0xf bank_mask:0xf
	v_mov_b32_dpp v100, v88 row_shr:1 row_mask:0xf bank_mask:0xf
	v_fma_f32 v106, v48, v108, v64
	v_fmac_f32_e32 v106, v52, v100
	v_fmac_f32_e32 v106, v88, v56
	v_mul_f32_e32 v96, v107, v96
	v_mul_f32_e32 v96, v106, v96
	v_mov_b32_e32 v106, 0
	v_mov_b32_e32 v100, 0
	v_mov_b32_e32 v107, 0
	v_mov_b32_dpp v106, v101 row_ror:2 row_mask:0xf bank_mask:0xf
	v_mov_b32_dpp v100, v101 row_ror:1 row_mask:0xf bank_mask:0xf
	v_mov_b32_e32 v101, 0
	v_mov_b32_dpp v106, v93 row_shr:2 row_mask:0xf bank_mask:0xf
	v_mov_b32_dpp v100, v93 row_shr:1 row_mask:0xf bank_mask:0xf
	v_fma_f32 v106, v69, v106, v61
	v_fmac_f32_e32 v106, v73, v100
	v_fmac_f32_e32 v106, v93, v77
	v_mul_f32_e32 v100, 0xbfb8aa3b, v106
	v_exp_f32_e32 v100, v100
	v_mov_b32_dpp v101, v97 row_ror:1 row_mask:0xf bank_mask:0xf
	v_mov_b32_dpp v107, v97 row_ror:2 row_mask:0xf bank_mask:0xf
	v_mov_b32_e32 v130, 0
	v_add_f32_e32 v97, 1.0, v100
	v_rcp_f32_e32 v97, v97
	v_mov_b32_dpp v107, v89 row_shr:2 row_mask:0xf bank_mask:0xf
	v_mov_b32_dpp v101, v89 row_shr:1 row_mask:0xf bank_mask:0xf
	v_fma_f32 v100, v49, v107, v65
	v_fmac_f32_e32 v100, v53, v101
	v_fmac_f32_e32 v100, v89, v57
	v_mul_f32_e32 v97, v106, v97
	v_mov_b32_e32 v101, 0
	v_mul_f32_e32 v97, v100, v97
	v_mov_b32_e32 v100, 0
	v_mov_b32_dpp v101, v102 row_ror:2 row_mask:0xf bank_mask:0xf
	v_mov_b32_e32 v106, 0
	v_mov_b32_dpp v100, v102 row_ror:1 row_mask:0xf bank_mask:0xf
	v_mov_b32_dpp v101, v94 row_shr:2 row_mask:0xf bank_mask:0xf
	v_fma_f32 v101, v70, v101, v62
	v_mov_b32_dpp v100, v94 row_shr:1 row_mask:0xf bank_mask:0xf
	v_fmac_f32_e32 v101, v74, v100
	v_fmac_f32_e32 v101, v94, v78
	v_mul_f32_e32 v100, 0xbfb8aa3b, v101
	v_exp_f32_e32 v100, v100
	v_mov_b32_e32 v102, 0
	v_mov_b32_dpp v106, v98 row_ror:2 row_mask:0xf bank_mask:0xf
	v_cvt_pk_bf16_f32 v146, v96, v97
	v_mov_b32_dpp v102, v98 row_ror:1 row_mask:0xf bank_mask:0xf
	v_add_f32_e32 v98, 1.0, v100
	v_rcp_f32_e32 v98, v98
	v_mov_b32_dpp v106, v90 row_shr:2 row_mask:0xf bank_mask:0xf
	v_mov_b32_dpp v102, v90 row_shr:1 row_mask:0xf bank_mask:0xf
	v_fma_f32 v100, v50, v106, v66
	v_fmac_f32_e32 v100, v54, v102
	v_fmac_f32_e32 v100, v90, v58
	v_mul_f32_e32 v98, v101, v98
	v_mov_b32_e32 v101, 0
	v_mul_f32_e32 v98, v100, v98
	v_mov_b32_e32 v100, 0
	v_mov_b32_dpp v101, v103 row_ror:2 row_mask:0xf bank_mask:0xf
	v_mov_b32_e32 v102, 0
	v_mov_b32_dpp v100, v103 row_ror:1 row_mask:0xf bank_mask:0xf
	v_mov_b32_dpp v101, v95 row_shr:2 row_mask:0xf bank_mask:0xf
	v_fma_f32 v101, v71, v101, v63
	v_mov_b32_dpp v100, v95 row_shr:1 row_mask:0xf bank_mask:0xf
	v_fmac_f32_e32 v101, v75, v100
	v_fmac_f32_e32 v101, v95, v79
	v_mul_f32_e32 v100, 0xbfb8aa3b, v101
	v_exp_f32_e32 v100, v100
	v_mov_b32_e32 v103, 0
	v_mov_b32_dpp v102, v99 row_ror:1 row_mask:0xf bank_mask:0xf
	v_mov_b32_e32 v97, 0
	v_mov_b32_dpp v103, v99 row_ror:2 row_mask:0xf bank_mask:0xf
	v_add_f32_e32 v99, 1.0, v100
	v_rcp_f32_e32 v99, v99
	v_mov_b32_dpp v103, v91 row_shr:2 row_mask:0xf bank_mask:0xf
	v_mov_b32_dpp v102, v91 row_shr:1 row_mask:0xf bank_mask:0xf
	v_fma_f32 v100, v51, v103, v67
	v_fmac_f32_e32 v100, v55, v102
	v_fmac_f32_e32 v100, v91, v59
	v_mul_f32_e32 v99, v101, v99
	v_mul_f32_e32 v99, v100, v99
	v_cvt_pk_bf16_f32 v147, v98, v99
	v_mov_b32_e32 v144, v244
	v_mov_b32_e32 v145, v245
	global_store_dwordx4 v[196:197], v[144:147], off
	v_mov_b32_e32 v96, 0
	v_mov_b32_dpp v97, v92 row_ror:2 row_mask:0xf bank_mask:0xf
	v_mov_b32_e32 v98, 0
	v_mov_b32_dpp v96, v92 row_ror:1 row_mask:0xf bank_mask:0xf
	v_mov_b32_dpp v97, v84 row_shr:2 row_mask:0xf bank_mask:0xf
	v_fma_f32 v97, v68, v97, v60
	v_mov_b32_dpp v96, v84 row_shr:1 row_mask:0xf bank_mask:0xf
	v_fmac_f32_e32 v97, v72, v96
	v_fmac_f32_e32 v97, v84, v76
	v_mul_f32_e32 v96, 0xbfb8aa3b, v97
	v_exp_f32_e32 v96, v96
	v_mov_b32_e32 v92, 0
	v_mov_b32_dpp v98, v88 row_ror:2 row_mask:0xf bank_mask:0xf
	v_mov_b32_e32 v131, 0
	v_mov_b32_dpp v92, v88 row_ror:1 row_mask:0xf bank_mask:0xf
	v_add_f32_e32 v88, 1.0, v96
	v_rcp_f32_e32 v88, v88
	v_mov_b32_dpp v98, v80 row_shr:2 row_mask:0xf bank_mask:0xf
	v_mov_b32_dpp v92, v80 row_shr:1 row_mask:0xf bank_mask:0xf
	v_fma_f32 v96, v48, v98, v64
	v_fmac_f32_e32 v96, v52, v92
	v_fmac_f32_e32 v96, v80, v56
	v_mul_f32_e32 v88, v97, v88
	v_mul_f32_e32 v88, v96, v88
	v_mov_b32_e32 v96, 0
	v_mov_b32_e32 v92, 0
	v_mov_b32_e32 v97, 0
	v_mov_b32_dpp v96, v93 row_ror:2 row_mask:0xf bank_mask:0xf
	v_mov_b32_dpp v92, v93 row_ror:1 row_mask:0xf bank_mask:0xf
	v_mov_b32_e32 v93, 0
	v_mov_b32_dpp v96, v85 row_shr:2 row_mask:0xf bank_mask:0xf
	v_mov_b32_dpp v92, v85 row_shr:1 row_mask:0xf bank_mask:0xf
	v_fma_f32 v96, v69, v96, v61
	v_fmac_f32_e32 v96, v73, v92
	v_fmac_f32_e32 v96, v85, v77
	v_mul_f32_e32 v92, 0xbfb8aa3b, v96
	v_exp_f32_e32 v92, v92
	v_mov_b32_dpp v93, v89 row_ror:1 row_mask:0xf bank_mask:0xf
	v_mov_b32_dpp v97, v89 row_ror:2 row_mask:0xf bank_mask:0xf
	v_add_f32_e32 v89, 1.0, v92
	v_rcp_f32_e32 v89, v89
	v_mov_b32_dpp v97, v81 row_shr:2 row_mask:0xf bank_mask:0xf
	v_mov_b32_dpp v93, v81 row_shr:1 row_mask:0xf bank_mask:0xf
	v_fma_f32 v92, v49, v97, v65
	v_fmac_f32_e32 v92, v53, v93
	v_fmac_f32_e32 v92, v81, v57
	v_mul_f32_e32 v89, v96, v89
	v_mov_b32_e32 v93, 0
	v_mul_f32_e32 v89, v92, v89
	v_mov_b32_e32 v92, 0
	v_mov_b32_dpp v93, v94 row_ror:2 row_mask:0xf bank_mask:0xf
	v_mov_b32_e32 v96, 0
	v_mov_b32_dpp v92, v94 row_ror:1 row_mask:0xf bank_mask:0xf
	v_mov_b32_dpp v93, v86 row_shr:2 row_mask:0xf bank_mask:0xf
	v_fma_f32 v93, v70, v93, v62
	v_mov_b32_dpp v92, v86 row_shr:1 row_mask:0xf bank_mask:0xf
	v_fmac_f32_e32 v93, v74, v92
	v_fmac_f32_e32 v93, v86, v78
	v_mul_f32_e32 v92, 0xbfb8aa3b, v93
	v_exp_f32_e32 v92, v92
	v_mov_b32_e32 v94, 0
	v_mov_b32_dpp v96, v90 row_ror:2 row_mask:0xf bank_mask:0xf
	v_cvt_pk_bf16_f32 v146, v88, v89
	v_mov_b32_dpp v94, v90 row_ror:1 row_mask:0xf bank_mask:0xf
	v_add_f32_e32 v90, 1.0, v92
	v_rcp_f32_e32 v90, v90
	v_mov_b32_dpp v96, v82 row_shr:2 row_mask:0xf bank_mask:0xf
	v_mov_b32_dpp v94, v82 row_shr:1 row_mask:0xf bank_mask:0xf
	v_fma_f32 v92, v50, v96, v66
	v_fmac_f32_e32 v92, v54, v94
	v_fmac_f32_e32 v92, v82, v58
	v_mul_f32_e32 v90, v93, v90
	v_mov_b32_e32 v93, 0
	v_mul_f32_e32 v90, v92, v90
	v_mov_b32_e32 v92, 0
	v_mov_b32_dpp v93, v95 row_ror:2 row_mask:0xf bank_mask:0xf
	v_mov_b32_e32 v94, 0
	v_mov_b32_dpp v92, v95 row_ror:1 row_mask:0xf bank_mask:0xf
	v_mov_b32_dpp v93, v87 row_shr:2 row_mask:0xf bank_mask:0xf
	v_fma_f32 v93, v71, v93, v63
	v_mov_b32_dpp v92, v87 row_shr:1 row_mask:0xf bank_mask:0xf
	v_fmac_f32_e32 v93, v75, v92
	v_fmac_f32_e32 v93, v87, v79
	v_mul_f32_e32 v92, 0xbfb8aa3b, v93
	v_exp_f32_e32 v92, v92
	v_mov_b32_e32 v95, 0
	v_mov_b32_dpp v94, v91 row_ror:1 row_mask:0xf bank_mask:0xf
	v_mov_b32_e32 v89, 0
	v_mov_b32_dpp v95, v91 row_ror:2 row_mask:0xf bank_mask:0xf
	v_add_f32_e32 v91, 1.0, v92
	v_rcp_f32_e32 v91, v91
	v_mov_b32_dpp v95, v83 row_shr:2 row_mask:0xf bank_mask:0xf
	v_mov_b32_dpp v94, v83 row_shr:1 row_mask:0xf bank_mask:0xf
	v_fma_f32 v92, v51, v95, v67
	v_fmac_f32_e32 v92, v55, v94
	v_fmac_f32_e32 v92, v83, v59
	v_mul_f32_e32 v91, v93, v91
	v_mul_f32_e32 v91, v92, v91
	v_cvt_pk_bf16_f32 v147, v90, v91
	v_mov_b32_e32 v144, v242
	v_mov_b32_e32 v145, v243
	global_store_dwordx4 v[184:185], v[144:147], off
	v_mov_b32_e32 v88, 0
	v_mov_b32_dpp v89, v84 row_ror:2 row_mask:0xf bank_mask:0xf
	v_mov_b32_e32 v90, 0
	v_mov_b32_dpp v88, v84 row_ror:1 row_mask:0xf bank_mask:0xf
	v_mov_b32_dpp v89, v44 row_shr:2 row_mask:0xf bank_mask:0xf
	v_fma_f32 v89, v68, v89, v60
	v_mov_b32_dpp v88, v44 row_shr:1 row_mask:0xf bank_mask:0xf
	v_fmac_f32_e32 v89, v72, v88
	v_fmac_f32_e32 v89, v44, v76
	v_mul_f32_e32 v88, 0xbfb8aa3b, v89
	v_exp_f32_e32 v88, v88
	v_mov_b32_e32 v84, 0
	v_mov_b32_dpp v90, v80 row_ror:2 row_mask:0xf bank_mask:0xf
	s_nop 0
	v_mov_b32_dpp v84, v80 row_ror:1 row_mask:0xf bank_mask:0xf
	v_add_f32_e32 v80, 1.0, v88
	v_rcp_f32_e32 v80, v80
	v_mov_b32_dpp v90, v36 row_shr:2 row_mask:0xf bank_mask:0xf
	v_mov_b32_dpp v84, v36 row_shr:1 row_mask:0xf bank_mask:0xf
	v_fma_f32 v88, v48, v90, v64
	v_fmac_f32_e32 v88, v52, v84
	v_fmac_f32_e32 v88, v36, v56
	v_mul_f32_e32 v80, v89, v80
	v_mul_f32_e32 v80, v88, v80
	v_mov_b32_e32 v88, 0
	v_mov_b32_e32 v84, 0
	v_mov_b32_e32 v89, 0
	v_mov_b32_dpp v88, v85 row_ror:2 row_mask:0xf bank_mask:0xf
	v_mov_b32_dpp v84, v85 row_ror:1 row_mask:0xf bank_mask:0xf
	v_mov_b32_e32 v85, 0
	v_mov_b32_dpp v88, v45 row_shr:2 row_mask:0xf bank_mask:0xf
	v_mov_b32_dpp v84, v45 row_shr:1 row_mask:0xf bank_mask:0xf
	v_fma_f32 v88, v69, v88, v61
	v_fmac_f32_e32 v88, v73, v84
	v_fmac_f32_e32 v88, v45, v77
	v_mul_f32_e32 v84, 0xbfb8aa3b, v88
	v_exp_f32_e32 v84, v84
	v_mov_b32_dpp v85, v81 row_ror:1 row_mask:0xf bank_mask:0xf
	v_mov_b32_dpp v89, v81 row_ror:2 row_mask:0xf bank_mask:0xf
	v_add_f32_e32 v81, 1.0, v84
	v_rcp_f32_e32 v81, v81
	v_mov_b32_dpp v89, v37 row_shr:2 row_mask:0xf bank_mask:0xf
	v_mov_b32_dpp v85, v37 row_shr:1 row_mask:0xf bank_mask:0xf
	v_fma_f32 v84, v49, v89, v65
	v_fmac_f32_e32 v84, v53, v85
	v_fmac_f32_e32 v84, v37, v57
	v_mul_f32_e32 v81, v88, v81
	v_mov_b32_e32 v85, 0
	v_mul_f32_e32 v81, v84, v81
	v_mov_b32_e32 v84, 0
	v_mov_b32_dpp v85, v86 row_ror:2 row_mask:0xf bank_mask:0xf
	v_mov_b32_e32 v88, 0
	v_mov_b32_dpp v84, v86 row_ror:1 row_mask:0xf bank_mask:0xf
	v_mov_b32_dpp v85, v46 row_shr:2 row_mask:0xf bank_mask:0xf
	v_fma_f32 v85, v70, v85, v62
	v_mov_b32_dpp v84, v46 row_shr:1 row_mask:0xf bank_mask:0xf
	v_fmac_f32_e32 v85, v74, v84
	v_fmac_f32_e32 v85, v46, v78
	v_mul_f32_e32 v84, 0xbfb8aa3b, v85
	v_exp_f32_e32 v84, v84
	v_mov_b32_e32 v86, 0
	v_mov_b32_dpp v88, v82 row_ror:2 row_mask:0xf bank_mask:0xf
	v_cvt_pk_bf16_f32 v146, v80, v81
	v_mov_b32_dpp v86, v82 row_ror:1 row_mask:0xf bank_mask:0xf
	v_add_f32_e32 v82, 1.0, v84
	v_rcp_f32_e32 v82, v82
	v_mov_b32_dpp v88, v38 row_shr:2 row_mask:0xf bank_mask:0xf
	v_mov_b32_dpp v86, v38 row_shr:1 row_mask:0xf bank_mask:0xf
	v_fma_f32 v84, v50, v88, v66
	v_fmac_f32_e32 v84, v54, v86
	v_fmac_f32_e32 v84, v38, v58
	v_mul_f32_e32 v82, v85, v82
	v_mov_b32_e32 v85, 0
	v_mul_f32_e32 v82, v84, v82
	v_mov_b32_e32 v84, 0
	v_mov_b32_dpp v85, v87 row_ror:2 row_mask:0xf bank_mask:0xf
	v_mov_b32_e32 v86, 0
	v_mov_b32_dpp v84, v87 row_ror:1 row_mask:0xf bank_mask:0xf
	v_mov_b32_dpp v85, v47 row_shr:2 row_mask:0xf bank_mask:0xf
	v_fma_f32 v85, v71, v85, v63
	v_mov_b32_dpp v84, v47 row_shr:1 row_mask:0xf bank_mask:0xf
	v_fmac_f32_e32 v85, v75, v84
	v_fmac_f32_e32 v85, v47, v79
	v_mul_f32_e32 v84, 0xbfb8aa3b, v85
	v_exp_f32_e32 v84, v84
	v_mov_b32_e32 v87, 0
	v_mov_b32_dpp v86, v83 row_ror:1 row_mask:0xf bank_mask:0xf
	v_mov_b32_e32 v81, 0
	v_mov_b32_dpp v87, v83 row_ror:2 row_mask:0xf bank_mask:0xf
	v_add_f32_e32 v83, 1.0, v84
	v_rcp_f32_e32 v83, v83
	v_mov_b32_dpp v87, v39 row_shr:2 row_mask:0xf bank_mask:0xf
	v_mov_b32_dpp v86, v39 row_shr:1 row_mask:0xf bank_mask:0xf
	v_fma_f32 v84, v51, v87, v67
	v_fmac_f32_e32 v84, v55, v86
	v_fmac_f32_e32 v84, v39, v59
	v_mul_f32_e32 v83, v85, v83
	v_mul_f32_e32 v83, v84, v83
	v_cvt_pk_bf16_f32 v147, v82, v83
	v_mov_b32_e32 v144, v200
	v_mov_b32_e32 v145, v201
	global_store_dwordx4 v[176:177], v[144:147], off
	v_mov_b32_e32 v80, 0
	v_mov_b32_dpp v81, v44 row_ror:2 row_mask:0xf bank_mask:0xf
	s_nop 0
	v_mov_b32_dpp v80, v44 row_ror:1 row_mask:0xf bank_mask:0xf
	v_mov_b32_dpp v81, v40 row_shr:2 row_mask:0xf bank_mask:0xf
	v_fma_f32 v81, v68, v81, v60
	v_mov_b32_dpp v80, v40 row_shr:1 row_mask:0xf bank_mask:0xf
	v_fmac_f32_e32 v81, v72, v80
	v_fmac_f32_e32 v81, v40, v76
	v_mul_f32_e32 v40, 0xbfb8aa3b, v81
	v_exp_f32_e32 v40, v40
	v_mov_b32_e32 v44, 0
	v_mov_b32_e32 v80, 0
	s_nop 0
	v_mov_b32_dpp v44, v36 row_ror:1 row_mask:0xf bank_mask:0xf
	v_mov_b32_dpp v80, v36 row_ror:2 row_mask:0xf bank_mask:0xf
	v_add_f32_e32 v36, 1.0, v40
	v_rcp_f32_e32 v36, v36
	v_mov_b32_dpp v80, v32 row_shr:2 row_mask:0xf bank_mask:0xf
	v_mov_b32_dpp v44, v32 row_shr:1 row_mask:0xf bank_mask:0xf
	v_fma_f32 v40, v48, v80, v64
	v_fmac_f32_e32 v40, v52, v44
	v_fmac_f32_e32 v40, v32, v56
	v_mul_f32_e32 v32, v81, v36
	v_mul_f32_e32 v32, v40, v32
	v_mov_b32_e32 v40, 0
	v_mov_b32_e32 v36, 0
	v_mov_b32_e32 v44, 0
	v_mov_b32_dpp v40, v45 row_ror:2 row_mask:0xf bank_mask:0xf
	v_mov_b32_dpp v36, v45 row_ror:1 row_mask:0xf bank_mask:0xf
	v_mov_b32_dpp v44, v37 row_ror:1 row_mask:0xf bank_mask:0xf
	v_mov_b32_dpp v40, v41 row_shr:2 row_mask:0xf bank_mask:0xf
	v_mov_b32_dpp v36, v41 row_shr:1 row_mask:0xf bank_mask:0xf
	v_fma_f32 v40, v69, v40, v61
	v_fmac_f32_e32 v40, v73, v36
	v_fmac_f32_e32 v40, v41, v77
	v_mul_f32_e32 v36, 0xbfb8aa3b, v40
	v_exp_f32_e32 v36, v36
	v_mov_b32_e32 v41, 0
	v_mov_b32_dpp v44, v33 row_shr:1 row_mask:0xf bank_mask:0xf
	v_add_f32_e32 v36, 1.0, v36
	v_mov_b32_dpp v41, v37 row_ror:2 row_mask:0xf bank_mask:0xf
	v_rcp_f32_e32 v36, v36
	s_nop 0
	v_mov_b32_dpp v41, v33 row_shr:2 row_mask:0xf bank_mask:0xf
	v_fma_f32 v37, v49, v41, v65
	v_fmac_f32_e32 v37, v53, v44
	v_fmac_f32_e32 v37, v33, v57
	v_mul_f32_e32 v33, v40, v36
	v_mul_f32_e32 v33, v37, v33
	v_mov_b32_e32 v37, 0
	v_mov_b32_e32 v36, 0
	v_mov_b32_e32 v41, 0
	v_mov_b32_dpp v37, v46 row_ror:2 row_mask:0xf bank_mask:0xf
	v_mov_b32_dpp v36, v46 row_ror:1 row_mask:0xf bank_mask:0xf
	v_mov_b32_e32 v40, 0
	v_mov_b32_dpp v37, v42 row_shr:2 row_mask:0xf bank_mask:0xf
	v_mov_b32_dpp v36, v42 row_shr:1 row_mask:0xf bank_mask:0xf
	v_fma_f32 v37, v70, v37, v62
	v_fmac_f32_e32 v37, v74, v36
	v_fmac_f32_e32 v37, v42, v78
	v_mul_f32_e32 v36, 0xbfb8aa3b, v37
	v_exp_f32_e32 v36, v36
	v_mov_b32_dpp v41, v38 row_ror:2 row_mask:0xf bank_mask:0xf
	v_mov_b32_dpp v40, v38 row_ror:1 row_mask:0xf bank_mask:0xf
	v_cvt_pk_bf16_f32 v146, v32, v33
	v_add_f32_e32 v36, 1.0, v36
	v_rcp_f32_e32 v36, v36
	v_mov_b32_dpp v41, v34 row_shr:2 row_mask:0xf bank_mask:0xf
	v_mov_b32_dpp v40, v34 row_shr:1 row_mask:0xf bank_mask:0xf
	v_fma_f32 v38, v50, v41, v66
	v_fmac_f32_e32 v38, v54, v40
	v_fmac_f32_e32 v38, v34, v58
	v_mul_f32_e32 v34, v37, v36
	v_mov_b32_e32 v37, 0
	v_mov_b32_e32 v36, 0
	v_mov_b32_e32 v40, 0
	v_mov_b32_dpp v37, v47 row_ror:2 row_mask:0xf bank_mask:0xf
	v_mov_b32_dpp v36, v47 row_ror:1 row_mask:0xf bank_mask:0xf
	v_mul_f32_e32 v34, v38, v34
	v_mov_b32_dpp v37, v43 row_shr:2 row_mask:0xf bank_mask:0xf
	v_mov_b32_dpp v36, v43 row_shr:1 row_mask:0xf bank_mask:0xf
	v_fma_f32 v37, v71, v37, v63
	v_fmac_f32_e32 v37, v75, v36
	v_fmac_f32_e32 v37, v43, v79
	v_mul_f32_e32 v36, 0xbfb8aa3b, v37
	v_exp_f32_e32 v36, v36
	v_mov_b32_e32 v38, 0
	v_mov_b32_dpp v40, v39 row_ror:2 row_mask:0xf bank_mask:0xf
	v_add_f32_e32 v36, 1.0, v36
	v_rcp_f32_e32 v36, v36
	v_mov_b32_dpp v38, v39 row_ror:1 row_mask:0xf bank_mask:0xf
	v_mov_b32_dpp v40, v35 row_shr:2 row_mask:0xf bank_mask:0xf
	v_fma_f32 v39, v51, v40, v67
	v_mov_b32_dpp v38, v35 row_shr:1 row_mask:0xf bank_mask:0xf
	v_fmac_f32_e32 v39, v55, v38
	v_fmac_f32_e32 v39, v35, v59
	v_mul_f32_e32 v35, v37, v36
	v_mul_f32_e32 v35, v39, v35
	v_cvt_pk_bf16_f32 v147, v34, v35
	v_mov_b32_e32 v144, v226
	v_mov_b32_e32 v145, v227
	global_store_dwordx4 v[134:135], v[144:147], off
	v_mov_b32_e32 v32, 0
	v_mov_b32_e32 v33, 0
	v_mov_b32_e32 v34, 0
	v_mov_b32_e32 v35, 0
	s_and_saveexec_b64 s[54:55], s[4:5]
	s_cbranch_execz .LBB0_721
	ds_read_b128 v[128:131], v237
	ds_read_b128 v[32:35], v236
.LBB0_721:
	s_or_b64 exec, exec, s[54:55]
	v_mov_b32_e32 v37, 0
	v_mov_b32_e32 v36, 0
	v_mov_b32_e32 v38, 0
	s_waitcnt lgkmcnt(1)
	v_mov_b32_dpp v37, v128 row_ror:2 row_mask:0xf bank_mask:0xf
	v_mov_b32_dpp v36, v128 row_ror:1 row_mask:0xf bank_mask:0xf
	v_mov_b32_e32 v39, 0
	v_mov_b32_dpp v37, v28 row_shr:2 row_mask:0xf bank_mask:0xf
	v_mov_b32_dpp v36, v28 row_shr:1 row_mask:0xf bank_mask:0xf
	v_fma_f32 v37, v68, v37, v60
	v_fmac_f32_e32 v37, v72, v36
	v_fmac_f32_e32 v37, v28, v76
	v_mul_f32_e32 v36, 0xbfb8aa3b, v37
	v_exp_f32_e32 v36, v36
	s_waitcnt lgkmcnt(0)
	v_mov_b32_dpp v38, v32 row_ror:1 row_mask:0xf bank_mask:0xf
	v_mov_b32_dpp v39, v32 row_ror:2 row_mask:0xf bank_mask:0xf
	s_andn2_b64 vcc, exec, s[8:9]
	v_add_f32_e32 v32, 1.0, v36
	v_rcp_f32_e32 v32, v32
	v_mov_b32_dpp v39, v24 row_shr:2 row_mask:0xf bank_mask:0xf
	v_mov_b32_dpp v38, v24 row_shr:1 row_mask:0xf bank_mask:0xf
	v_fma_f32 v36, v48, v39, v64
	v_fmac_f32_e32 v36, v52, v38
	v_fmac_f32_e32 v36, v24, v56
	v_mul_f32_e32 v32, v37, v32
	v_mov_b32_e32 v37, 0
	v_mul_f32_e32 v32, v36, v32
	v_mov_b32_e32 v36, 0
	v_mov_b32_dpp v37, v129 row_ror:2 row_mask:0xf bank_mask:0xf
	v_mov_b32_e32 v38, 0
	v_mov_b32_dpp v36, v129 row_ror:1 row_mask:0xf bank_mask:0xf
	v_mov_b32_dpp v37, v29 row_shr:2 row_mask:0xf bank_mask:0xf
	v_fma_f32 v37, v69, v37, v61
	v_mov_b32_dpp v36, v29 row_shr:1 row_mask:0xf bank_mask:0xf
	v_fmac_f32_e32 v37, v73, v36
	v_fmac_f32_e32 v37, v29, v77
	v_mul_f32_e32 v36, 0xbfb8aa3b, v37
	v_exp_f32_e32 v36, v36
	v_mov_b32_e32 v39, 0
	v_mov_b32_dpp v38, v33 row_ror:1 row_mask:0xf bank_mask:0xf
	s_mov_b64 s[8:9], -1
	v_mov_b32_dpp v39, v33 row_ror:2 row_mask:0xf bank_mask:0xf
	v_add_f32_e32 v33, 1.0, v36
	v_rcp_f32_e32 v33, v33
	v_mov_b32_dpp v39, v25 row_shr:2 row_mask:0xf bank_mask:0xf
	v_mov_b32_dpp v38, v25 row_shr:1 row_mask:0xf bank_mask:0xf
	v_fma_f32 v36, v49, v39, v65
	v_fmac_f32_e32 v36, v53, v38
	v_fmac_f32_e32 v36, v25, v57
	v_mul_f32_e32 v33, v37, v33
	v_mov_b32_e32 v37, 0
	v_mul_f32_e32 v33, v36, v33
	v_mov_b32_e32 v36, 0
	v_mov_b32_dpp v37, v130 row_ror:2 row_mask:0xf bank_mask:0xf
	v_mov_b32_e32 v38, 0
	v_mov_b32_dpp v36, v130 row_ror:1 row_mask:0xf bank_mask:0xf
	v_mov_b32_dpp v37, v30 row_shr:2 row_mask:0xf bank_mask:0xf
	v_fma_f32 v37, v70, v37, v62
	v_mov_b32_dpp v36, v30 row_shr:1 row_mask:0xf bank_mask:0xf
	v_fmac_f32_e32 v37, v74, v36
	v_fmac_f32_e32 v37, v30, v78
	v_mul_f32_e32 v36, 0xbfb8aa3b, v37
	v_exp_f32_e32 v36, v36
	v_mov_b32_e32 v39, 0
	v_mov_b32_dpp v38, v34 row_ror:1 row_mask:0xf bank_mask:0xf
	v_cvt_pk_bf16_f32 v146, v32, v33
	v_mov_b32_dpp v39, v34 row_ror:2 row_mask:0xf bank_mask:0xf
	v_add_f32_e32 v34, 1.0, v36
	v_rcp_f32_e32 v34, v34
	v_mov_b32_dpp v39, v26 row_shr:2 row_mask:0xf bank_mask:0xf
	v_mov_b32_dpp v38, v26 row_shr:1 row_mask:0xf bank_mask:0xf
	v_fma_f32 v36, v50, v39, v66
	v_fmac_f32_e32 v36, v54, v38
	v_fmac_f32_e32 v36, v26, v58
	v_mul_f32_e32 v34, v37, v34
	v_mov_b32_e32 v37, 0
	v_mul_f32_e32 v34, v36, v34
	v_mov_b32_e32 v36, 0
	v_mov_b32_dpp v37, v131 row_ror:2 row_mask:0xf bank_mask:0xf
	v_mov_b32_e32 v38, 0
	v_mov_b32_dpp v36, v131 row_ror:1 row_mask:0xf bank_mask:0xf
	v_mov_b32_dpp v37, v31 row_shr:2 row_mask:0xf bank_mask:0xf
	v_fma_f32 v37, v71, v37, v63
	v_mov_b32_dpp v36, v31 row_shr:1 row_mask:0xf bank_mask:0xf
	v_fmac_f32_e32 v37, v75, v36
	v_fmac_f32_e32 v37, v31, v79
	v_mul_f32_e32 v36, 0xbfb8aa3b, v37
	v_exp_f32_e32 v36, v36
	v_mov_b32_e32 v39, 0
	v_mov_b32_dpp v38, v35 row_ror:1 row_mask:0xf bank_mask:0xf
	v_mov_b32_e32 v33, 0
	v_mov_b32_dpp v39, v35 row_ror:2 row_mask:0xf bank_mask:0xf
	v_add_f32_e32 v35, 1.0, v36
	v_rcp_f32_e32 v35, v35
	v_mov_b32_dpp v39, v27 row_shr:2 row_mask:0xf bank_mask:0xf
	v_mov_b32_dpp v38, v27 row_shr:1 row_mask:0xf bank_mask:0xf
	v_fma_f32 v36, v51, v39, v67
	v_fmac_f32_e32 v36, v55, v38
	v_fmac_f32_e32 v36, v27, v59
	v_mul_f32_e32 v35, v37, v35
	v_mul_f32_e32 v35, v36, v35
	v_cvt_pk_bf16_f32 v147, v34, v35
	v_mov_b32_e32 v144, v186
	v_mov_b32_e32 v145, v187
	global_store_dwordx4 v[132:133], v[144:147], off
	v_mov_b32_e32 v32, 0
	v_mov_b32_dpp v33, v28 row_ror:2 row_mask:0xf bank_mask:0xf
	v_mov_b32_e32 v34, 0
	v_mov_b32_dpp v32, v28 row_ror:1 row_mask:0xf bank_mask:0xf
	v_mov_b32_dpp v33, v20 row_shr:2 row_mask:0xf bank_mask:0xf
	v_fma_f32 v33, v68, v33, v60
	v_mov_b32_dpp v32, v20 row_shr:1 row_mask:0xf bank_mask:0xf
	v_fmac_f32_e32 v33, v72, v32
	v_fmac_f32_e32 v33, v20, v76
	v_mul_f32_e32 v32, 0xbfb8aa3b, v33
	v_exp_f32_e32 v32, v32
	v_mov_b32_e32 v28, 0
	v_mov_b32_dpp v34, v24 row_ror:2 row_mask:0xf bank_mask:0xf
	s_nop 0
	v_mov_b32_dpp v28, v24 row_ror:1 row_mask:0xf bank_mask:0xf
	v_add_f32_e32 v24, 1.0, v32
	v_rcp_f32_e32 v24, v24
	v_mov_b32_dpp v34, v16 row_shr:2 row_mask:0xf bank_mask:0xf
	v_mov_b32_dpp v28, v16 row_shr:1 row_mask:0xf bank_mask:0xf
	v_fma_f32 v32, v48, v34, v64
	v_fmac_f32_e32 v32, v52, v28
	v_fmac_f32_e32 v32, v16, v56
	v_mul_f32_e32 v24, v33, v24
	v_mul_f32_e32 v24, v32, v24
	v_mov_b32_e32 v32, 0
	v_mov_b32_e32 v28, 0
	v_mov_b32_e32 v33, 0
	v_mov_b32_dpp v32, v29 row_ror:2 row_mask:0xf bank_mask:0xf
	v_mov_b32_dpp v28, v29 row_ror:1 row_mask:0xf bank_mask:0xf
	v_mov_b32_e32 v29, 0
	v_mov_b32_dpp v32, v21 row_shr:2 row_mask:0xf bank_mask:0xf
	v_mov_b32_dpp v28, v21 row_shr:1 row_mask:0xf bank_mask:0xf
	v_fma_f32 v32, v69, v32, v61
	v_fmac_f32_e32 v32, v73, v28
	v_fmac_f32_e32 v32, v21, v77
	v_mul_f32_e32 v28, 0xbfb8aa3b, v32
	v_exp_f32_e32 v28, v28
	v_mov_b32_dpp v29, v25 row_ror:1 row_mask:0xf bank_mask:0xf
	v_mov_b32_dpp v33, v25 row_ror:2 row_mask:0xf bank_mask:0xf
	v_add_f32_e32 v25, 1.0, v28
	v_rcp_f32_e32 v25, v25
	v_mov_b32_dpp v33, v17 row_shr:2 row_mask:0xf bank_mask:0xf
	v_mov_b32_dpp v29, v17 row_shr:1 row_mask:0xf bank_mask:0xf
	v_fma_f32 v28, v49, v33, v65
	v_fmac_f32_e32 v28, v53, v29
	v_fmac_f32_e32 v28, v17, v57
	v_mul_f32_e32 v25, v32, v25
	v_mov_b32_e32 v29, 0
	v_mul_f32_e32 v25, v28, v25
	v_mov_b32_e32 v28, 0
	v_mov_b32_dpp v29, v30 row_ror:2 row_mask:0xf bank_mask:0xf
	v_mov_b32_e32 v32, 0
	v_mov_b32_dpp v28, v30 row_ror:1 row_mask:0xf bank_mask:0xf
	v_mov_b32_dpp v29, v22 row_shr:2 row_mask:0xf bank_mask:0xf
	v_fma_f32 v29, v70, v29, v62
	v_mov_b32_dpp v28, v22 row_shr:1 row_mask:0xf bank_mask:0xf
	v_fmac_f32_e32 v29, v74, v28
	v_fmac_f32_e32 v29, v22, v78
	v_mul_f32_e32 v28, 0xbfb8aa3b, v29
	v_exp_f32_e32 v28, v28
	v_mov_b32_e32 v30, 0
	v_mov_b32_dpp v32, v26 row_ror:2 row_mask:0xf bank_mask:0xf
	v_cvt_pk_bf16_f32 v146, v24, v25
	v_mov_b32_dpp v30, v26 row_ror:1 row_mask:0xf bank_mask:0xf
	v_add_f32_e32 v26, 1.0, v28
	v_rcp_f32_e32 v26, v26
	v_mov_b32_dpp v32, v18 row_shr:2 row_mask:0xf bank_mask:0xf
	v_mov_b32_dpp v30, v18 row_shr:1 row_mask:0xf bank_mask:0xf
	v_fma_f32 v28, v50, v32, v66
	v_fmac_f32_e32 v28, v54, v30
	v_fmac_f32_e32 v28, v18, v58
	v_mul_f32_e32 v26, v29, v26
	v_mov_b32_e32 v29, 0
	v_mul_f32_e32 v26, v28, v26
	v_mov_b32_e32 v28, 0
	v_mov_b32_dpp v29, v31 row_ror:2 row_mask:0xf bank_mask:0xf
	v_mov_b32_e32 v30, 0
	v_mov_b32_dpp v28, v31 row_ror:1 row_mask:0xf bank_mask:0xf
	v_mov_b32_dpp v29, v23 row_shr:2 row_mask:0xf bank_mask:0xf
	v_fma_f32 v29, v71, v29, v63
	v_mov_b32_dpp v28, v23 row_shr:1 row_mask:0xf bank_mask:0xf
	v_fmac_f32_e32 v29, v75, v28
	v_fmac_f32_e32 v29, v23, v79
	v_mul_f32_e32 v28, 0xbfb8aa3b, v29
	v_exp_f32_e32 v28, v28
	v_mov_b32_e32 v31, 0
	v_mov_b32_dpp v30, v27 row_ror:1 row_mask:0xf bank_mask:0xf
	v_mov_b32_e32 v25, 0
	v_mov_b32_dpp v31, v27 row_ror:2 row_mask:0xf bank_mask:0xf
	v_add_f32_e32 v27, 1.0, v28
	v_rcp_f32_e32 v27, v27
	v_mov_b32_dpp v31, v19 row_shr:2 row_mask:0xf bank_mask:0xf
	v_mov_b32_dpp v30, v19 row_shr:1 row_mask:0xf bank_mask:0xf
	v_fma_f32 v28, v51, v31, v67
	v_fmac_f32_e32 v28, v55, v30
	v_fmac_f32_e32 v28, v19, v59
	v_mul_f32_e32 v27, v29, v27
	v_mul_f32_e32 v27, v28, v27
	v_cvt_pk_bf16_f32 v147, v26, v27
	v_mov_b32_e32 v144, v188
	v_mov_b32_e32 v145, v189
	global_store_dwordx4 v[120:121], v[144:147], off
	v_mov_b32_e32 v24, 0
	v_mov_b32_dpp v25, v20 row_ror:2 row_mask:0xf bank_mask:0xf
	v_mov_b32_e32 v26, 0
	v_mov_b32_dpp v24, v20 row_ror:1 row_mask:0xf bank_mask:0xf
	v_mov_b32_dpp v25, v12 row_shr:2 row_mask:0xf bank_mask:0xf
	v_fma_f32 v25, v68, v25, v60
	v_mov_b32_dpp v24, v12 row_shr:1 row_mask:0xf bank_mask:0xf
	v_fmac_f32_e32 v25, v72, v24
	v_fmac_f32_e32 v25, v12, v76
	v_mul_f32_e32 v24, 0xbfb8aa3b, v25
	v_exp_f32_e32 v24, v24
	v_mov_b32_e32 v20, 0
	v_mov_b32_dpp v26, v16 row_ror:2 row_mask:0xf bank_mask:0xf
	s_nop 0
	v_mov_b32_dpp v20, v16 row_ror:1 row_mask:0xf bank_mask:0xf
	v_add_f32_e32 v16, 1.0, v24
	v_rcp_f32_e32 v16, v16
	v_mov_b32_dpp v26, v4 row_shr:2 row_mask:0xf bank_mask:0xf
	v_mov_b32_dpp v20, v4 row_shr:1 row_mask:0xf bank_mask:0xf
	v_fma_f32 v24, v48, v26, v64
	v_fmac_f32_e32 v24, v52, v20
	v_fmac_f32_e32 v24, v4, v56
	v_mul_f32_e32 v16, v25, v16
	v_mul_f32_e32 v16, v24, v16
	v_mov_b32_e32 v24, 0
	v_mov_b32_e32 v20, 0
	v_mov_b32_e32 v25, 0
	v_mov_b32_dpp v24, v21 row_ror:2 row_mask:0xf bank_mask:0xf
	v_mov_b32_dpp v20, v21 row_ror:1 row_mask:0xf bank_mask:0xf
	v_mov_b32_e32 v21, 0
	v_mov_b32_dpp v24, v13 row_shr:2 row_mask:0xf bank_mask:0xf
	v_mov_b32_dpp v20, v13 row_shr:1 row_mask:0xf bank_mask:0xf
	v_fma_f32 v24, v69, v24, v61
	v_fmac_f32_e32 v24, v73, v20
	v_fmac_f32_e32 v24, v13, v77
	v_mul_f32_e32 v20, 0xbfb8aa3b, v24
	v_exp_f32_e32 v20, v20
	v_mov_b32_dpp v21, v17 row_ror:1 row_mask:0xf bank_mask:0xf
	v_mov_b32_dpp v25, v17 row_ror:2 row_mask:0xf bank_mask:0xf
	v_add_f32_e32 v17, 1.0, v20
	v_rcp_f32_e32 v17, v17
	v_mov_b32_dpp v25, v5 row_shr:2 row_mask:0xf bank_mask:0xf
	v_mov_b32_dpp v21, v5 row_shr:1 row_mask:0xf bank_mask:0xf
	v_fma_f32 v20, v49, v25, v65
	v_fmac_f32_e32 v20, v53, v21
	v_fmac_f32_e32 v20, v5, v57
	v_mul_f32_e32 v17, v24, v17
	v_mov_b32_e32 v21, 0
	v_mul_f32_e32 v17, v20, v17
	v_mov_b32_e32 v20, 0
	v_mov_b32_dpp v21, v22 row_ror:2 row_mask:0xf bank_mask:0xf
	v_mov_b32_e32 v24, 0
	v_mov_b32_dpp v20, v22 row_ror:1 row_mask:0xf bank_mask:0xf
	v_mov_b32_dpp v21, v14 row_shr:2 row_mask:0xf bank_mask:0xf
	v_fma_f32 v21, v70, v21, v62
	v_mov_b32_dpp v20, v14 row_shr:1 row_mask:0xf bank_mask:0xf
	v_fmac_f32_e32 v21, v74, v20
	v_fmac_f32_e32 v21, v14, v78
	v_mul_f32_e32 v20, 0xbfb8aa3b, v21
	v_exp_f32_e32 v20, v20
	v_mov_b32_e32 v22, 0
	v_mov_b32_dpp v24, v18 row_ror:2 row_mask:0xf bank_mask:0xf
	v_cvt_pk_bf16_f32 v146, v16, v17
	v_mov_b32_dpp v22, v18 row_ror:1 row_mask:0xf bank_mask:0xf
	v_add_f32_e32 v18, 1.0, v20
	v_rcp_f32_e32 v18, v18
	v_mov_b32_dpp v24, v6 row_shr:2 row_mask:0xf bank_mask:0xf
	v_mov_b32_dpp v22, v6 row_shr:1 row_mask:0xf bank_mask:0xf
	v_fma_f32 v20, v50, v24, v66
	v_fmac_f32_e32 v20, v54, v22
	v_fmac_f32_e32 v20, v6, v58
	v_mul_f32_e32 v18, v21, v18
	v_mov_b32_e32 v21, 0
	v_mul_f32_e32 v18, v20, v18
	v_mov_b32_e32 v20, 0
	v_mov_b32_dpp v21, v23 row_ror:2 row_mask:0xf bank_mask:0xf
	v_mov_b32_e32 v22, 0
	v_mov_b32_dpp v20, v23 row_ror:1 row_mask:0xf bank_mask:0xf
	v_mov_b32_dpp v21, v15 row_shr:2 row_mask:0xf bank_mask:0xf
	v_fma_f32 v21, v71, v21, v63
	v_mov_b32_dpp v20, v15 row_shr:1 row_mask:0xf bank_mask:0xf
	v_fmac_f32_e32 v21, v75, v20
	v_fmac_f32_e32 v21, v15, v79
	v_mul_f32_e32 v20, 0xbfb8aa3b, v21
	v_exp_f32_e32 v20, v20
	v_mov_b32_e32 v23, 0
	v_mov_b32_dpp v22, v19 row_ror:1 row_mask:0xf bank_mask:0xf
	v_mov_b32_e32 v17, 0
	v_mov_b32_dpp v23, v19 row_ror:2 row_mask:0xf bank_mask:0xf
	v_add_f32_e32 v19, 1.0, v20
	v_rcp_f32_e32 v19, v19
	v_mov_b32_dpp v23, v7 row_shr:2 row_mask:0xf bank_mask:0xf
	v_mov_b32_dpp v22, v7 row_shr:1 row_mask:0xf bank_mask:0xf
	v_fma_f32 v20, v51, v23, v67
	v_fmac_f32_e32 v20, v55, v22
	v_fmac_f32_e32 v20, v7, v59
	v_mul_f32_e32 v19, v21, v19
	v_mul_f32_e32 v19, v20, v19
	v_cvt_pk_bf16_f32 v147, v18, v19
	v_mov_b32_e32 v144, v190
	v_mov_b32_e32 v145, v191
	global_store_dwordx4 v[112:113], v[144:147], off
	v_mov_b32_e32 v16, 0
	v_mov_b32_dpp v17, v12 row_ror:2 row_mask:0xf bank_mask:0xf
	s_nop 0
	v_mov_b32_dpp v16, v12 row_ror:1 row_mask:0xf bank_mask:0xf
	v_mov_b32_dpp v17, v8 row_shr:2 row_mask:0xf bank_mask:0xf
	v_fma_f32 v17, v68, v17, v60
	v_mov_b32_dpp v16, v8 row_shr:1 row_mask:0xf bank_mask:0xf
	v_fmac_f32_e32 v17, v72, v16
	v_fmac_f32_e32 v17, v8, v76
	v_mul_f32_e32 v8, 0xbfb8aa3b, v17
	v_exp_f32_e32 v8, v8
	v_mov_b32_e32 v12, 0
	v_mov_b32_e32 v16, 0
	s_nop 0
	v_mov_b32_dpp v12, v4 row_ror:1 row_mask:0xf bank_mask:0xf
	v_mov_b32_dpp v16, v4 row_ror:2 row_mask:0xf bank_mask:0xf
	v_add_f32_e32 v4, 1.0, v8
	v_rcp_f32_e32 v4, v4
	v_mov_b32_dpp v16, v0 row_shr:2 row_mask:0xf bank_mask:0xf
	v_mov_b32_dpp v12, v0 row_shr:1 row_mask:0xf bank_mask:0xf
	v_fma_f32 v8, v48, v16, v64
	v_fmac_f32_e32 v8, v52, v12
	v_fmac_f32_e32 v8, v0, v56
	v_mul_f32_e32 v0, v17, v4
	v_mul_f32_e32 v0, v8, v0
	v_mov_b32_e32 v8, 0
	v_mov_b32_e32 v4, 0
	v_mov_b32_e32 v12, 0
	v_mov_b32_dpp v8, v13 row_ror:2 row_mask:0xf bank_mask:0xf
	v_mov_b32_dpp v4, v13 row_ror:1 row_mask:0xf bank_mask:0xf
	v_mov_b32_dpp v12, v5 row_ror:1 row_mask:0xf bank_mask:0xf
	v_mov_b32_dpp v8, v9 row_shr:2 row_mask:0xf bank_mask:0xf
	v_mov_b32_dpp v4, v9 row_shr:1 row_mask:0xf bank_mask:0xf
	v_fma_f32 v8, v69, v8, v61
	v_fmac_f32_e32 v8, v73, v4
	v_fmac_f32_e32 v8, v9, v77
	v_mul_f32_e32 v4, 0xbfb8aa3b, v8
	v_exp_f32_e32 v4, v4
	v_mov_b32_e32 v9, 0
	v_mov_b32_dpp v12, v1 row_shr:1 row_mask:0xf bank_mask:0xf
	v_add_f32_e32 v4, 1.0, v4
	v_mov_b32_dpp v9, v5 row_ror:2 row_mask:0xf bank_mask:0xf
	v_rcp_f32_e32 v4, v4
	s_nop 0
	v_mov_b32_dpp v9, v1 row_shr:2 row_mask:0xf bank_mask:0xf
	v_fma_f32 v5, v49, v9, v65
	v_fmac_f32_e32 v5, v53, v12
	v_fmac_f32_e32 v5, v1, v57
	v_mul_f32_e32 v1, v8, v4
	v_mul_f32_e32 v1, v5, v1
	v_mov_b32_e32 v5, 0
	v_mov_b32_e32 v4, 0
	v_mov_b32_e32 v9, 0
	v_mov_b32_dpp v5, v14 row_ror:2 row_mask:0xf bank_mask:0xf
	v_mov_b32_dpp v4, v14 row_ror:1 row_mask:0xf bank_mask:0xf
	v_mov_b32_e32 v8, 0
	v_mov_b32_dpp v5, v10 row_shr:2 row_mask:0xf bank_mask:0xf
	v_mov_b32_dpp v4, v10 row_shr:1 row_mask:0xf bank_mask:0xf
	v_fma_f32 v5, v70, v5, v62
	v_fmac_f32_e32 v5, v74, v4
	v_fmac_f32_e32 v5, v10, v78
	v_mul_f32_e32 v4, 0xbfb8aa3b, v5
	v_exp_f32_e32 v4, v4
	v_mov_b32_dpp v9, v6 row_ror:2 row_mask:0xf bank_mask:0xf
	v_mov_b32_dpp v8, v6 row_ror:1 row_mask:0xf bank_mask:0xf
	v_cvt_pk_bf16_f32 v146, v0, v1
	v_add_f32_e32 v4, 1.0, v4
	v_rcp_f32_e32 v4, v4
	v_mov_b32_dpp v9, v2 row_shr:2 row_mask:0xf bank_mask:0xf
	v_mov_b32_dpp v8, v2 row_shr:1 row_mask:0xf bank_mask:0xf
	v_fma_f32 v6, v50, v9, v66
	v_fmac_f32_e32 v6, v54, v8
	v_fmac_f32_e32 v6, v2, v58
	v_mul_f32_e32 v2, v5, v4
	v_mov_b32_e32 v5, 0
	v_mov_b32_e32 v4, 0
	v_mul_f32_e32 v2, v6, v2
	v_mov_b32_dpp v5, v15 row_ror:2 row_mask:0xf bank_mask:0xf
	v_mov_b32_dpp v4, v15 row_ror:1 row_mask:0xf bank_mask:0xf
	v_mov_b32_e32 v6, 0
	v_mov_b32_dpp v5, v11 row_shr:2 row_mask:0xf bank_mask:0xf
	v_mov_b32_dpp v4, v11 row_shr:1 row_mask:0xf bank_mask:0xf
	v_fmac_f32_e32 v63, v71, v5
	v_fmac_f32_e32 v63, v75, v4
	v_fmac_f32_e32 v63, v11, v79
	v_mul_f32_e32 v4, 0xbfb8aa3b, v63
	v_exp_f32_e32 v4, v4
	v_mov_b32_e32 v5, 0
	v_mov_b32_dpp v6, v7 row_ror:1 row_mask:0xf bank_mask:0xf
	v_add_f32_e32 v4, 1.0, v4
	v_mov_b32_dpp v5, v7 row_ror:2 row_mask:0xf bank_mask:0xf
	v_rcp_f32_e32 v4, v4
	v_mov_b32_dpp v6, v3 row_shr:1 row_mask:0xf bank_mask:0xf
	v_mov_b32_dpp v5, v3 row_shr:2 row_mask:0xf bank_mask:0xf
	v_fmac_f32_e32 v67, v51, v5
	v_fmac_f32_e32 v67, v55, v6
	v_fmac_f32_e32 v67, v3, v59
	v_mul_f32_e32 v3, v63, v4
	v_mul_f32_e32 v3, v67, v3
	v_cvt_pk_bf16_f32 v147, v2, v3
	v_mov_b32_e32 v144, v192
	v_mov_b32_e32 v145, v193
	global_store_dwordx4 v[104:105], v[144:147], off
	s_cbranch_vccnz .LBB0_701
	s_and_b64 vcc, exec, s[10:11]
	s_cbranch_vccnz .LBB0_700
	s_barrier
	s_branch .LBB0_700
	s_nop 0
	s_nop 0
	s_nop 0
	s_nop 0
	s_nop 0
	s_nop 0
	s_nop 0
	s_nop 0
	s_nop 0
	s_nop 0
	s_nop 0
	s_nop 0
	s_nop 0
	s_nop 0
	s_nop 0
	s_nop 0
	s_nop 0
	s_nop 0
	s_nop 0
	s_nop 0
	s_nop 0
	s_nop 0
	s_nop 0
	s_nop 0
	s_nop 0
	s_nop 0
	s_nop 0
	s_nop 0
	s_nop 0
	s_nop 0
	s_nop 0
	s_nop 0
